# nt on the prologue's bf16 weight tile stores
# baseline (speedup 1.0000x reference)
; #define LAS __attribute__((address_space(3)))
; __device__ __forceinline__ unsigned cvt_pk_bf16(float lo, float hi) { const f32x2 v = {lo, hi}; return __builtin_bit_cast(unsigned, __builtin_convertvector(v, bfx2_t)); }
; __device__ __forceinline__ void convT_tile(const float* src, int ldsrc, const float* sc, bf16_t* dst, int dstld, int k0, int n0, int swiglu, LAS float* t) {
;     const int tid = threadIdx.x;
;     { const int r = tid >> 6, c4 = (tid & 63) * 4;
;       int ncol = n0 + c4; if (swiglu) { const int blk = n0 >> 8; ncol = (c4 < 128) ? (128 * blk + c4) : (FF + 128 * blk + (c4 - 128)); }
;       f32x4 v[8]; float sv[8];
; #pragma unroll
;       for (int i = 0; i < 8; ++i) { const int rr = r + 8 * i; v[i] = *(const f32x4*)(src + (size_t)(k0 + rr) * ldsrc + ncol); sv[i] = sc ? sc[k0 + rr] : 1.0f; }
; #pragma unroll
;       for (int i = 0; i < 8; ++i) { const int rr = r + 8 * i; t[rr * 257 + c4 + 0] = v[i][0] * sv[i]; t[rr * 257 + c4 + 1] = v[i][1] * sv[i]; t[rr * 257 + c4 + 2] = v[i][2] * sv[i]; t[rr * 257 + c4 + 3] = v[i][3] * sv[i]; } }
;     __syncthreads();
;     { const int nn = tid >> 1, kh = (tid & 1) * 32;
; #pragma unroll
;       for (int q = 0; q < 4; ++q) { float v[8];
; #pragma unroll
;           for (int j = 0; j < 8; ++j) v[j] = t[(kh + q * 8 + j) * 257 + nn];
;           u32x4 w; w.x = cvt_pk_bf16(v[0], v[1]); w.y = cvt_pk_bf16(v[2], v[3]); w.z = cvt_pk_bf16(v[4], v[5]); w.w = cvt_pk_bf16(v[6], v[7]);
;           *(u32x4*)(dst + (size_t)(n0 + nn) * dstld + k0 + kh + q * 8) = w; } }
;     __syncthreads();
; }
.LBB0_17:
	s_waitcnt vmcnt(7)
	v_pk_mul_f32 v[2:3], v[2:3], v[46:47] op_sel_hi:[1,0]
	ds_write2_b32 v53, v2, v3 offset1:1
	v_pk_mul_f32 v[2:3], v[4:5], v[46:47] op_sel_hi:[1,0]
	ds_write2_b32 v53, v2, v3 offset0:2 offset1:3
	s_waitcnt vmcnt(6)
	v_pk_mul_f32 v[2:3], v[6:7], v[42:43] op_sel_hi:[1,0]
	v_add_u32_e32 v4, 0x2020, v53
	ds_write2_b32 v4, v2, v3 offset1:1
	v_pk_mul_f32 v[2:3], v[8:9], v[42:43] op_sel_hi:[1,0]
	v_add_u32_e32 v4, 0x2028, v53
	ds_write2_b32 v4, v2, v3 offset1:1
	s_waitcnt vmcnt(5)
	v_pk_mul_f32 v[2:3], v[10:11], v[52:53] op_sel_hi:[1,0]
	v_add_u32_e32 v4, 0x4040, v53
	ds_write2_b32 v4, v2, v3 offset1:1
	v_pk_mul_f32 v[2:3], v[12:13], v[52:53] op_sel_hi:[1,0]
	v_add_u32_e32 v4, 0x4048, v53
	ds_write2_b32 v4, v2, v3 offset1:1
	s_waitcnt vmcnt(4)
	v_pk_mul_f32 v[2:3], v[14:15], v[44:45] op_sel_hi:[1,0]
	v_add_u32_e32 v4, 0x6060, v53
	ds_write2_b32 v4, v2, v3 offset1:1
	v_pk_mul_f32 v[2:3], v[16:17], v[44:45] op_sel_hi:[1,0]
	v_add_u32_e32 v4, 0x6068, v53
	ds_write2_b32 v4, v2, v3 offset1:1
	s_waitcnt vmcnt(3)
	v_pk_mul_f32 v[2:3], v[18:19], v[56:57] op_sel_hi:[1,0]
	v_add_u32_e32 v4, 0x8080, v53
	ds_write2_b32 v4, v2, v3 offset1:1
	v_pk_mul_f32 v[2:3], v[20:21], v[56:57] op_sel_hi:[1,0]
	v_add_u32_e32 v4, 0x8088, v53
	ds_write2_b32 v4, v2, v3 offset1:1
	s_waitcnt vmcnt(2)
	v_pk_mul_f32 v[2:3], v[22:23], v[48:49] op_sel_hi:[1,0]
	v_add_u32_e32 v4, 0xa0a0, v53
	ds_write2_b32 v4, v2, v3 offset1:1
	v_pk_mul_f32 v[2:3], v[24:25], v[48:49] op_sel_hi:[1,0]
	v_add_u32_e32 v4, 0xa0a8, v53
	ds_write2_b32 v4, v2, v3 offset1:1
	s_waitcnt vmcnt(1)
	v_pk_mul_f32 v[2:3], v[26:27], v[58:59] op_sel_hi:[1,0]
	v_add_u32_e32 v4, 0xc0c0, v53
	ds_write2_b32 v4, v2, v3 offset1:1
	v_pk_mul_f32 v[2:3], v[28:29], v[58:59] op_sel_hi:[1,0]
	v_add_u32_e32 v4, 0xc0c8, v53
	ds_write2_b32 v4, v2, v3 offset1:1
	s_waitcnt vmcnt(0)
	v_pk_mul_f32 v[2:3], v[30:31], v[54:55] op_sel_hi:[1,0]
	v_add_u32_e32 v4, 0xe0e0, v53
	ds_write2_b32 v4, v2, v3 offset1:1
	v_pk_mul_f32 v[2:3], v[32:33], v[54:55] op_sel_hi:[1,0]
	v_add_u32_e32 v4, 0xe0e8, v53
	ds_write2_b32 v4, v2, v3 offset1:1
	s_waitcnt lgkmcnt(0)
	s_barrier
	v_lshl_add_u32 v2, s80, 8, v55
	ds_read_b32 v4, v57
	ds_read_b32 v5, v57 offset:1028
	ds_read_b32 v8, v57 offset:2056
	ds_read_b32 v9, v57 offset:3084
	ds_read_b32 v10, v57 offset:4112
	ds_read_b32 v11, v57 offset:5140
	ds_read_b32 v12, v57 offset:6168
	ds_read_b32 v13, v57 offset:7196
	v_ashrrev_i32_e32 v3, 31, v2
	s_add_i32 s0, s39, s0
	v_lshlrev_b64 v[2:3], 11, v[2:3]
	v_lshl_add_u64 v[2:3], s[40:41], 0, v[2:3]
	s_ashr_i32 s1, s0, 31
	v_lshl_add_u64 v[2:3], s[0:1], 1, v[2:3]
	v_lshl_add_u64 v[6:7], v[2:3], 0, v[34:35]
	s_waitcnt lgkmcnt(6)
	v_cvt_pk_bf16_f32 v2, v4, v5
	s_waitcnt lgkmcnt(4)
	v_cvt_pk_bf16_f32 v3, v8, v9
	s_waitcnt lgkmcnt(2)
	v_cvt_pk_bf16_f32 v4, v10, v11
	s_waitcnt lgkmcnt(0)
	v_cvt_pk_bf16_f32 v5, v12, v13
	ds_read_b32 v8, v57 offset:8224
	ds_read_b32 v9, v57 offset:9252
	ds_read_b32 v10, v57 offset:10280
	ds_read_b32 v11, v57 offset:11308
	ds_read_b32 v12, v57 offset:12336
	ds_read_b32 v13, v57 offset:13364
	ds_read_b32 v14, v57 offset:14392
	ds_read_b32 v15, v57 offset:15420
	global_store_dwordx4 v[6:7], v[2:5], off nt
	s_add_i32 s26, s26, s88
	s_add_i32 s39, s39, s5
	s_waitcnt lgkmcnt(6)
	v_cvt_pk_bf16_f32 v2, v8, v9
	s_waitcnt lgkmcnt(4)
	v_cvt_pk_bf16_f32 v3, v10, v11
	s_waitcnt lgkmcnt(2)
	v_cvt_pk_bf16_f32 v4, v12, v13
	s_waitcnt lgkmcnt(0)
	v_cvt_pk_bf16_f32 v5, v14, v15
	ds_read_b32 v8, v57 offset:16448
	ds_read_b32 v9, v57 offset:17476
	ds_read_b32 v10, v57 offset:18504
	ds_read_b32 v11, v57 offset:19532
	ds_read_b32 v12, v57 offset:20560
	ds_read_b32 v13, v57 offset:21588
	ds_read_b32 v14, v57 offset:22616
	ds_read_b32 v15, v57 offset:23644
	global_store_dwordx4 v[6:7], v[2:5], off offset:16 nt
	s_cmpk_lt_i32 s26, 0x160
	s_waitcnt lgkmcnt(6)
	v_cvt_pk_bf16_f32 v2, v8, v9
	s_waitcnt lgkmcnt(4)
	v_cvt_pk_bf16_f32 v3, v10, v11
	s_waitcnt lgkmcnt(2)
	v_cvt_pk_bf16_f32 v4, v12, v13
	s_waitcnt lgkmcnt(0)
	v_cvt_pk_bf16_f32 v5, v14, v15
	ds_read_b32 v8, v57 offset:24672
	ds_read_b32 v9, v57 offset:25700
	ds_read_b32 v10, v57 offset:26728
	ds_read_b32 v11, v57 offset:27756
	ds_read_b32 v12, v57 offset:28784
	ds_read_b32 v13, v57 offset:29812
	ds_read_b32 v14, v57 offset:30840
	ds_read_b32 v15, v57 offset:31868
	global_store_dwordx4 v[6:7], v[2:5], off offset:32 nt
	s_waitcnt lgkmcnt(6)
	s_nop 0
	v_cvt_pk_bf16_f32 v2, v8, v9
	s_waitcnt lgkmcnt(4)
	v_cvt_pk_bf16_f32 v3, v10, v11
	s_waitcnt lgkmcnt(2)
	v_cvt_pk_bf16_f32 v4, v12, v13
	s_waitcnt lgkmcnt(0)
	v_cvt_pk_bf16_f32 v5, v14, v15
	global_store_dwordx4 v[6:7], v[2:5], off offset:48 nt
	s_barrier
	s_cbranch_scc0 .LBB0_34

; #define LAS __attribute__((address_space(3)))
; __device__ __forceinline__ unsigned cvt_pk_bf16(float lo, float hi) { const f32x2 v = {lo, hi}; return __builtin_bit_cast(unsigned, __builtin_convertvector(v, bfx2_t)); }
; __device__ __forceinline__ void convT_tile(const float* src, int ldsrc, const float* sc, bf16_t* dst, int dstld, int k0, int n0, int swiglu, LAS float* t) {
;     const int tid = threadIdx.x;
;     { const int r = tid >> 6, c4 = (tid & 63) * 4;
;       int ncol = n0 + c4; if (swiglu) { const int blk = n0 >> 8; ncol = (c4 < 128) ? (128 * blk + c4) : (FF + 128 * blk + (c4 - 128)); }
;       f32x4 v[8]; float sv[8];
; #pragma unroll
;       for (int i = 0; i < 8; ++i) { const int rr = r + 8 * i; v[i] = *(const f32x4*)(src + (size_t)(k0 + rr) * ldsrc + ncol); sv[i] = sc ? sc[k0 + rr] : 1.0f; }
; #pragma unroll
;       for (int i = 0; i < 8; ++i) { const int rr = r + 8 * i; t[rr * 257 + c4 + 0] = v[i][0] * sv[i]; t[rr * 257 + c4 + 1] = v[i][1] * sv[i]; t[rr * 257 + c4 + 2] = v[i][2] * sv[i]; t[rr * 257 + c4 + 3] = v[i][3] * sv[i]; } }
;     __syncthreads();
;     { const int nn = tid >> 1, kh = (tid & 1) * 32;
; #pragma unroll
;       for (int q = 0; q < 4; ++q) { float v[8];
; #pragma unroll
;           for (int j = 0; j < 8; ++j) v[j] = t[(kh + q * 8 + j) * 257 + nn];
;           u32x4 w; w.x = cvt_pk_bf16(v[0], v[1]); w.y = cvt_pk_bf16(v[2], v[3]); w.z = cvt_pk_bf16(v[4], v[5]); w.w = cvt_pk_bf16(v[6], v[7]);
;           *(u32x4*)(dst + (size_t)(n0 + nn) * dstld + k0 + kh + q * 8) = w; } }
;     __syncthreads();
; }
.LBB0_36:
	s_mul_hi_i32 s80, s26, 0x2e8ba2e9
	s_lshr_b32 s81, s80, 31
	s_ashr_i32 s80, s80, 3
	s_add_i32 s80, s80, s81
	s_mul_i32 s81, s80, 0xfffff500
	s_lshl_b32 s80, s80, 8
	s_add_i32 s90, s92, s81
	v_or_b32_e32 v2, s80, v45
	v_add_u32_e32 v4, s90, v37
	v_ashrrev_i32_e32 v3, 31, v2
	v_lshl_add_u64 v[6:7], v[2:3], 2, s[0:1]
	v_add_u32_e32 v2, 8, v4
	v_add_u32_e32 v8, 16, v4
	v_add_u32_e32 v10, 24, v4
	v_add_u32_e32 v12, 32, v4
	v_add_u32_e32 v14, 40, v4
	v_add_u32_e32 v16, 48, v4
	v_add_u32_e32 v18, 56, v4
	v_ashrrev_i32_e32 v5, 31, v4
	v_ashrrev_i32_e32 v3, 31, v2
	v_ashrrev_i32_e32 v9, 31, v8
	v_ashrrev_i32_e32 v11, 31, v10
	v_ashrrev_i32_e32 v13, 31, v12
	v_ashrrev_i32_e32 v15, 31, v14
	v_ashrrev_i32_e32 v17, 31, v16
	v_ashrrev_i32_e32 v19, 31, v18
	v_lshlrev_b64 v[4:5], 12, v[4:5]
	v_lshlrev_b64 v[20:21], 12, v[2:3]
	v_lshlrev_b64 v[8:9], 12, v[8:9]
	v_lshlrev_b64 v[10:11], 12, v[10:11]
	v_lshlrev_b64 v[12:13], 12, v[12:13]
	v_lshlrev_b64 v[14:15], 12, v[14:15]
	v_lshlrev_b64 v[16:17], 12, v[16:17]
	v_lshlrev_b64 v[18:19], 12, v[18:19]
	v_lshl_add_u64 v[4:5], v[6:7], 0, v[4:5]
	v_lshl_add_u64 v[20:21], v[6:7], 0, v[20:21]
	v_lshl_add_u64 v[22:23], v[6:7], 0, v[8:9]
	v_lshl_add_u64 v[24:25], v[6:7], 0, v[10:11]
	v_lshl_add_u64 v[26:27], v[6:7], 0, v[12:13]
	v_lshl_add_u64 v[28:29], v[6:7], 0, v[14:15]
	v_lshl_add_u64 v[30:31], v[6:7], 0, v[16:17]
	v_lshl_add_u64 v[32:33], v[6:7], 0, v[18:19]
	global_load_dwordx4 v[2:5], v[4:5], off nt
	s_nop 0
	global_load_dwordx4 v[6:9], v[20:21], off nt
	global_load_dwordx4 v[10:13], v[22:23], off nt
	global_load_dwordx4 v[14:17], v[24:25], off nt
	s_nop 0
	global_load_dwordx4 v[18:21], v[26:27], off nt
	global_load_dwordx4 v[22:25], v[28:29], off nt
	s_nop 0
	global_load_dwordx4 v[26:29], v[30:31], off nt
	s_nop 0
	global_load_dwordx4 v[30:33], v[32:33], off nt
	v_add_u32_e32 v41, 0x2020, v53
	v_add_u32_e32 v42, 0x2028, v53
	v_add_u32_e32 v44, 0x4040, v53
	v_add_u32_e32 v46, 0x4048, v53
	v_add_u32_e32 v50, 0x6060, v53
	v_add_u32_e32 v51, 0x6068, v53
	v_add_u32_e32 v52, 0x8080, v53
	v_add_u32_e32 v54, 0x8088, v53
	v_add_u32_e32 v56, 0xa0a0, v53
	v_add_u32_e32 v58, 0xa0a8, v53
	v_add_u32_e32 v65, 0xc0c0, v53
	v_add_u32_e32 v66, 0xc0c8, v53
	v_add_u32_e32 v67, 0xe0e0, v53
	v_add_u32_e32 v68, 0xe0e8, v53
	v_mov_b64_e32 v[48:49], s[44:45]
	v_add_u32_e32 v69, s80, v55
	v_mad_i64_i32 v[48:49], s[80:81], v69, s25, v[48:49]
	s_ashr_i32 s91, s90, 31
	s_add_i32 s26, s26, s88
	s_add_i32 s92, s92, s5
	v_lshl_add_u64 v[48:49], s[90:91], 1, v[48:49]
	s_cmpk_lt_i32 s26, 0xb0
	v_lshl_add_u64 v[48:49], v[48:49], 0, v[34:35]
	s_waitcnt vmcnt(7)
	ds_write2_b32 v53, v2, v3 offset1:1
	ds_write2_b32 v53, v4, v5 offset0:2 offset1:3
	s_waitcnt vmcnt(6)
	ds_write2_b32 v41, v6, v7 offset1:1
	ds_write2_b32 v42, v8, v9 offset1:1
	s_waitcnt vmcnt(5)
	ds_write2_b32 v44, v10, v11 offset1:1
	ds_write2_b32 v46, v12, v13 offset1:1
	s_waitcnt vmcnt(4)
	ds_write2_b32 v50, v14, v15 offset1:1
	ds_write2_b32 v51, v16, v17 offset1:1
	s_waitcnt vmcnt(3)
	ds_write2_b32 v52, v18, v19 offset1:1
	ds_write2_b32 v54, v20, v21 offset1:1
	s_waitcnt vmcnt(2)
	ds_write2_b32 v56, v22, v23 offset1:1
	ds_write2_b32 v58, v24, v25 offset1:1
	s_waitcnt vmcnt(1)
	ds_write2_b32 v65, v26, v27 offset1:1
	ds_write2_b32 v66, v28, v29 offset1:1
	s_waitcnt vmcnt(0)
	ds_write2_b32 v67, v30, v31 offset1:1
	ds_write2_b32 v68, v32, v33 offset1:1
	s_waitcnt lgkmcnt(0)
	s_barrier
	ds_read_b32 v2, v57
	ds_read_b32 v3, v57 offset:1028
	ds_read_b32 v4, v57 offset:2056
	ds_read_b32 v5, v57 offset:3084
	ds_read_b32 v6, v57 offset:4112
	ds_read_b32 v7, v57 offset:5140
	ds_read_b32 v8, v57 offset:6168
	ds_read_b32 v9, v57 offset:7196
	ds_read_b32 v10, v57 offset:8224
	ds_read_b32 v11, v57 offset:9252
	ds_read_b32 v12, v57 offset:10280
	ds_read_b32 v13, v57 offset:11308
	ds_read_b32 v14, v57 offset:12336
	ds_read_b32 v15, v57 offset:13364
	ds_read_b32 v16, v57 offset:14392
	ds_read_b32 v17, v57 offset:15420
	ds_read_b32 v18, v57 offset:16448
	ds_read_b32 v19, v57 offset:17476
	ds_read_b32 v20, v57 offset:18504
	ds_read_b32 v21, v57 offset:19532
	ds_read_b32 v22, v57 offset:20560
	ds_read_b32 v23, v57 offset:21588
	ds_read_b32 v24, v57 offset:22616
	ds_read_b32 v25, v57 offset:23644
	ds_read_b32 v26, v57 offset:24672
	ds_read_b32 v27, v57 offset:25700
	ds_read_b32 v28, v57 offset:26728
	ds_read_b32 v29, v57 offset:27756
	ds_read_b32 v30, v57 offset:28784
	ds_read_b32 v31, v57 offset:29812
	ds_read_b32 v32, v57 offset:30840
	ds_read_b32 v33, v57 offset:31868
	s_waitcnt lgkmcnt(14)
	v_cvt_pk_bf16_f32 v2, v2, v3
	v_cvt_pk_bf16_f32 v3, v4, v5
	v_cvt_pk_bf16_f32 v4, v6, v7
	v_cvt_pk_bf16_f32 v5, v8, v9
	v_cvt_pk_bf16_f32 v6, v10, v11
	v_cvt_pk_bf16_f32 v7, v12, v13
	v_cvt_pk_bf16_f32 v8, v14, v15
	v_cvt_pk_bf16_f32 v9, v16, v17
	v_cvt_pk_bf16_f32 v10, v18, v19
	s_waitcnt lgkmcnt(12)
	v_cvt_pk_bf16_f32 v11, v20, v21
	s_waitcnt lgkmcnt(10)
	v_cvt_pk_bf16_f32 v12, v22, v23
	s_waitcnt lgkmcnt(8)
	v_cvt_pk_bf16_f32 v13, v24, v25
	s_waitcnt lgkmcnt(6)
	v_cvt_pk_bf16_f32 v14, v26, v27
	s_waitcnt lgkmcnt(4)
	v_cvt_pk_bf16_f32 v15, v28, v29
	s_waitcnt lgkmcnt(2)
	v_cvt_pk_bf16_f32 v16, v30, v31
	s_waitcnt lgkmcnt(0)
	v_cvt_pk_bf16_f32 v17, v32, v33
	global_store_dwordx4 v[48:49], v[2:5], off nt
	global_store_dwordx4 v[48:49], v[6:9], off offset:16 nt
	global_store_dwordx4 v[48:49], v[10:13], off offset:32 nt
	global_store_dwordx4 v[48:49], v[14:17], off offset:48 nt
	s_barrier
	s_cbranch_scc1 .LBB0_36

; #define LAS __attribute__((address_space(3)))
; __device__ __forceinline__ unsigned cvt_pk_bf16(float lo, float hi) { const f32x2 v = {lo, hi}; return __builtin_bit_cast(unsigned, __builtin_convertvector(v, bfx2_t)); }
; __device__ __forceinline__ void convT_tile(const float* src, int ldsrc, const float* sc, bf16_t* dst, int dstld, int k0, int n0, int swiglu, LAS float* t) {
;     const int tid = threadIdx.x;
;     { const int r = tid >> 6, c4 = (tid & 63) * 4;
;       int ncol = n0 + c4; if (swiglu) { const int blk = n0 >> 8; ncol = (c4 < 128) ? (128 * blk + c4) : (FF + 128 * blk + (c4 - 128)); }
;       f32x4 v[8]; float sv[8];
; #pragma unroll
;       for (int i = 0; i < 8; ++i) { const int rr = r + 8 * i; v[i] = *(const f32x4*)(src + (size_t)(k0 + rr) * ldsrc + ncol); sv[i] = sc ? sc[k0 + rr] : 1.0f; }
; #pragma unroll
;       for (int i = 0; i < 8; ++i) { const int rr = r + 8 * i; t[rr * 257 + c4 + 0] = v[i][0] * sv[i]; t[rr * 257 + c4 + 1] = v[i][1] * sv[i]; t[rr * 257 + c4 + 2] = v[i][2] * sv[i]; t[rr * 257 + c4 + 3] = v[i][3] * sv[i]; } }
;     __syncthreads();
;     { const int nn = tid >> 1, kh = (tid & 1) * 32;
; #pragma unroll
;       for (int q = 0; q < 4; ++q) { float v[8];
; #pragma unroll
;           for (int j = 0; j < 8; ++j) v[j] = t[(kh + q * 8 + j) * 257 + nn];
;           u32x4 w; w.x = cvt_pk_bf16(v[0], v[1]); w.y = cvt_pk_bf16(v[2], v[3]); w.z = cvt_pk_bf16(v[4], v[5]); w.w = cvt_pk_bf16(v[6], v[7]);
;           *(u32x4*)(dst + (size_t)(n0 + nn) * dstld + k0 + kh + q * 8) = w; } }
;     __syncthreads();
; }
.LBB0_39:
	s_waitcnt vmcnt(7)
	v_pk_mul_f32 v[2:3], v[2:3], v[44:45] op_sel_hi:[1,0]
	ds_write2_b32 v53, v2, v3 offset1:1
	v_pk_mul_f32 v[2:3], v[4:5], v[44:45] op_sel_hi:[1,0]
	ds_write2_b32 v53, v2, v3 offset0:2 offset1:3
	s_waitcnt vmcnt(6)
	v_pk_mul_f32 v[2:3], v[6:7], v[42:43] op_sel_hi:[1,0]
	v_add_u32_e32 v4, 0x2020, v53
	ds_write2_b32 v4, v2, v3 offset1:1
	v_pk_mul_f32 v[2:3], v[8:9], v[42:43] op_sel_hi:[1,0]
	v_add_u32_e32 v4, 0x2028, v53
	ds_write2_b32 v4, v2, v3 offset1:1
	s_waitcnt vmcnt(5)
	v_pk_mul_f32 v[2:3], v[10:11], v[50:51] op_sel_hi:[1,0]
	v_add_u32_e32 v4, 0x4040, v53
	ds_write2_b32 v4, v2, v3 offset1:1
	v_pk_mul_f32 v[2:3], v[12:13], v[50:51] op_sel_hi:[1,0]
	v_add_u32_e32 v4, 0x4048, v53
	ds_write2_b32 v4, v2, v3 offset1:1
	s_waitcnt vmcnt(4)
	v_pk_mul_f32 v[2:3], v[14:15], v[46:47] op_sel_hi:[1,0]
	v_add_u32_e32 v4, 0x6060, v53
	ds_write2_b32 v4, v2, v3 offset1:1
	v_pk_mul_f32 v[2:3], v[16:17], v[46:47] op_sel_hi:[1,0]
	v_add_u32_e32 v4, 0x6068, v53
	ds_write2_b32 v4, v2, v3 offset1:1
	s_waitcnt vmcnt(3)
	v_pk_mul_f32 v[2:3], v[18:19], v[54:55] op_sel_hi:[1,0]
	v_add_u32_e32 v4, 0x8080, v53
	ds_write2_b32 v4, v2, v3 offset1:1
	v_pk_mul_f32 v[2:3], v[20:21], v[54:55] op_sel_hi:[1,0]
	v_add_u32_e32 v4, 0x8088, v53
	ds_write2_b32 v4, v2, v3 offset1:1
	s_waitcnt vmcnt(2)
	v_pk_mul_f32 v[2:3], v[22:23], v[52:53] op_sel_hi:[1,0]
	v_add_u32_e32 v4, 0xa0a0, v53
	ds_write2_b32 v4, v2, v3 offset1:1
	v_pk_mul_f32 v[2:3], v[24:25], v[52:53] op_sel_hi:[1,0]
	v_add_u32_e32 v4, 0xa0a8, v53
	ds_write2_b32 v4, v2, v3 offset1:1
	s_waitcnt vmcnt(1)
	v_pk_mul_f32 v[2:3], v[26:27], v[58:59] op_sel_hi:[1,0]
	v_add_u32_e32 v4, 0xc0c0, v53
	ds_write2_b32 v4, v2, v3 offset1:1
	v_pk_mul_f32 v[2:3], v[28:29], v[58:59] op_sel_hi:[1,0]
	v_add_u32_e32 v4, 0xc0c8, v53
	ds_write2_b32 v4, v2, v3 offset1:1
	s_waitcnt vmcnt(0)
	v_pk_mul_f32 v[2:3], v[30:31], v[56:57] op_sel_hi:[1,0]
	v_add_u32_e32 v4, 0xe0e0, v53
	ds_write2_b32 v4, v2, v3 offset1:1
	v_pk_mul_f32 v[2:3], v[32:33], v[56:57] op_sel_hi:[1,0]
	v_add_u32_e32 v4, 0xe0e8, v53
	ds_write2_b32 v4, v2, v3 offset1:1
	s_waitcnt lgkmcnt(0)
	s_barrier
	v_add_u32_e32 v2, s80, v55
	ds_read_b32 v4, v57
	ds_read_b32 v5, v57 offset:1028
	ds_read_b32 v8, v57 offset:2056
	ds_read_b32 v9, v57 offset:3084
	ds_read_b32 v10, v57 offset:4112
	ds_read_b32 v11, v57 offset:5140
	ds_read_b32 v12, v57 offset:6168
	ds_read_b32 v13, v57 offset:7196
	v_ashrrev_i32_e32 v3, 31, v2
	s_add_i32 s0, s39, s0
	v_lshlrev_b64 v[2:3], 11, v[2:3]
	v_lshl_add_u64 v[2:3], s[94:95], 0, v[2:3]
	s_ashr_i32 s1, s0, 31
	v_lshl_add_u64 v[2:3], s[0:1], 1, v[2:3]
	v_lshl_add_u64 v[6:7], v[2:3], 0, v[34:35]
	s_waitcnt lgkmcnt(6)
	v_cvt_pk_bf16_f32 v2, v4, v5
	s_waitcnt lgkmcnt(4)
	v_cvt_pk_bf16_f32 v3, v8, v9
	s_waitcnt lgkmcnt(2)
	v_cvt_pk_bf16_f32 v4, v10, v11
	s_waitcnt lgkmcnt(0)
	v_cvt_pk_bf16_f32 v5, v12, v13
	ds_read_b32 v8, v57 offset:8224
	ds_read_b32 v9, v57 offset:9252
	ds_read_b32 v10, v57 offset:10280
	ds_read_b32 v11, v57 offset:11308
	ds_read_b32 v12, v57 offset:12336
	ds_read_b32 v13, v57 offset:13364
	ds_read_b32 v14, v57 offset:14392
	ds_read_b32 v15, v57 offset:15420
	global_store_dwordx4 v[6:7], v[2:5], off nt
	s_add_i32 s26, s26, s88
	s_add_i32 s39, s39, s5
	s_waitcnt lgkmcnt(6)
	v_cvt_pk_bf16_f32 v2, v8, v9
	s_waitcnt lgkmcnt(4)
	v_cvt_pk_bf16_f32 v3, v10, v11
	s_waitcnt lgkmcnt(2)
	v_cvt_pk_bf16_f32 v4, v12, v13
	s_waitcnt lgkmcnt(0)
	v_cvt_pk_bf16_f32 v5, v14, v15
	ds_read_b32 v8, v57 offset:16448
	ds_read_b32 v9, v57 offset:17476
	ds_read_b32 v10, v57 offset:18504
	ds_read_b32 v11, v57 offset:19532
	ds_read_b32 v12, v57 offset:20560
	ds_read_b32 v13, v57 offset:21588
	ds_read_b32 v14, v57 offset:22616
	ds_read_b32 v15, v57 offset:23644
	global_store_dwordx4 v[6:7], v[2:5], off offset:16 nt
	s_cmp_lt_i32 s26, 64
	s_waitcnt lgkmcnt(6)
	v_cvt_pk_bf16_f32 v2, v8, v9
	s_waitcnt lgkmcnt(4)
	v_cvt_pk_bf16_f32 v3, v10, v11
	s_waitcnt lgkmcnt(2)
	v_cvt_pk_bf16_f32 v4, v12, v13
	s_waitcnt lgkmcnt(0)
	v_cvt_pk_bf16_f32 v5, v14, v15
	ds_read_b32 v8, v57 offset:24672
	ds_read_b32 v9, v57 offset:25700
	ds_read_b32 v10, v57 offset:26728
	ds_read_b32 v11, v57 offset:27756
	ds_read_b32 v12, v57 offset:28784
	ds_read_b32 v13, v57 offset:29812
	ds_read_b32 v14, v57 offset:30840
	ds_read_b32 v15, v57 offset:31868
	global_store_dwordx4 v[6:7], v[2:5], off offset:32 nt
	s_waitcnt lgkmcnt(6)
	s_nop 0
	v_cvt_pk_bf16_f32 v2, v8, v9
	s_waitcnt lgkmcnt(4)
	v_cvt_pk_bf16_f32 v3, v10, v11
	s_waitcnt lgkmcnt(2)
	v_cvt_pk_bf16_f32 v4, v12, v13
	s_waitcnt lgkmcnt(0)
	v_cvt_pk_bf16_f32 v5, v14, v15
	global_store_dwordx4 v[6:7], v[2:5], off offset:48 nt
	s_barrier
	s_cbranch_scc0 .LBB0_56

; #define LAS __attribute__((address_space(3)))
; __device__ __forceinline__ unsigned cvt_pk_bf16(float lo, float hi) { const f32x2 v = {lo, hi}; return __builtin_bit_cast(unsigned, __builtin_convertvector(v, bfx2_t)); }
; __device__ __forceinline__ void convT_tile(const float* src, int ldsrc, const float* sc, bf16_t* dst, int dstld, int k0, int n0, int swiglu, LAS float* t) {
;     const int tid = threadIdx.x;
;     { const int r = tid >> 6, c4 = (tid & 63) * 4;
;       int ncol = n0 + c4; if (swiglu) { const int blk = n0 >> 8; ncol = (c4 < 128) ? (128 * blk + c4) : (FF + 128 * blk + (c4 - 128)); }
;       f32x4 v[8]; float sv[8];
; #pragma unroll
;       for (int i = 0; i < 8; ++i) { const int rr = r + 8 * i; v[i] = *(const f32x4*)(src + (size_t)(k0 + rr) * ldsrc + ncol); sv[i] = sc ? sc[k0 + rr] : 1.0f; }
; #pragma unroll
;       for (int i = 0; i < 8; ++i) { const int rr = r + 8 * i; t[rr * 257 + c4 + 0] = v[i][0] * sv[i]; t[rr * 257 + c4 + 1] = v[i][1] * sv[i]; t[rr * 257 + c4 + 2] = v[i][2] * sv[i]; t[rr * 257 + c4 + 3] = v[i][3] * sv[i]; } }
;     __syncthreads();
;     { const int nn = tid >> 1, kh = (tid & 1) * 32;
; #pragma unroll
;       for (int q = 0; q < 4; ++q) { float v[8];
; #pragma unroll
;           for (int j = 0; j < 8; ++j) v[j] = t[(kh + q * 8 + j) * 257 + nn];
;           u32x4 w; w.x = cvt_pk_bf16(v[0], v[1]); w.y = cvt_pk_bf16(v[2], v[3]); w.z = cvt_pk_bf16(v[4], v[5]); w.w = cvt_pk_bf16(v[6], v[7]);
;           *(u32x4*)(dst + (size_t)(n0 + nn) * dstld + k0 + kh + q * 8) = w; } }
;     __syncthreads();
; }
.LBB0_58:
	s_ashr_i32 s80, s26, 31
	s_lshr_b32 s80, s80, 29
	s_add_i32 s80, s26, s80
	s_ashr_i32 s80, s80, 3
	s_lshl_b32 s81, s80, 9
	s_lshl_b32 s80, s80, 8
	s_sub_i32 s92, s39, s81
	v_or_b32_e32 v2, s80, v45
	v_add_u32_e32 v4, s92, v37
	v_ashrrev_i32_e32 v3, 31, v2
	v_lshl_add_u64 v[6:7], v[2:3], 2, s[0:1]
	v_add_u32_e32 v2, 8, v4
	v_add_u32_e32 v8, 16, v4
	v_add_u32_e32 v10, 24, v4
	v_add_u32_e32 v12, 32, v4
	v_add_u32_e32 v14, 40, v4
	v_add_u32_e32 v16, 48, v4
	v_add_u32_e32 v18, 56, v4
	v_ashrrev_i32_e32 v5, 31, v4
	v_ashrrev_i32_e32 v3, 31, v2
	v_ashrrev_i32_e32 v9, 31, v8
	v_ashrrev_i32_e32 v11, 31, v10
	v_ashrrev_i32_e32 v13, 31, v12
	v_ashrrev_i32_e32 v15, 31, v14
	v_ashrrev_i32_e32 v17, 31, v16
	v_ashrrev_i32_e32 v19, 31, v18
	v_lshlrev_b64 v[4:5], 11, v[4:5]
	v_lshlrev_b64 v[20:21], 11, v[2:3]
	v_lshlrev_b64 v[8:9], 11, v[8:9]
	v_lshlrev_b64 v[10:11], 11, v[10:11]
	v_lshlrev_b64 v[12:13], 11, v[12:13]
	v_lshlrev_b64 v[14:15], 11, v[14:15]
	v_lshlrev_b64 v[16:17], 11, v[16:17]
	v_lshlrev_b64 v[18:19], 11, v[18:19]
	v_lshl_add_u64 v[4:5], v[6:7], 0, v[4:5]
	v_lshl_add_u64 v[20:21], v[6:7], 0, v[20:21]
	v_lshl_add_u64 v[22:23], v[6:7], 0, v[8:9]
	v_lshl_add_u64 v[24:25], v[6:7], 0, v[10:11]
	v_lshl_add_u64 v[26:27], v[6:7], 0, v[12:13]
	v_lshl_add_u64 v[28:29], v[6:7], 0, v[14:15]
	v_lshl_add_u64 v[30:31], v[6:7], 0, v[16:17]
	v_lshl_add_u64 v[32:33], v[6:7], 0, v[18:19]
	global_load_dwordx4 v[2:5], v[4:5], off nt
	s_nop 0
	global_load_dwordx4 v[6:9], v[20:21], off nt
	global_load_dwordx4 v[10:13], v[22:23], off nt
	global_load_dwordx4 v[14:17], v[24:25], off nt
	s_nop 0
	global_load_dwordx4 v[18:21], v[26:27], off nt
	global_load_dwordx4 v[22:25], v[28:29], off nt
	s_nop 0
	global_load_dwordx4 v[26:29], v[30:31], off nt
	s_nop 0
	global_load_dwordx4 v[30:33], v[32:33], off nt
	v_add_u32_e32 v48, s80, v55
	v_add_u32_e32 v41, 0x2020, v53
	v_add_u32_e32 v42, 0x2028, v53
	v_add_u32_e32 v44, 0x4040, v53
	v_add_u32_e32 v46, 0x4048, v53
	v_add_u32_e32 v50, 0x6060, v53
	v_add_u32_e32 v51, 0x6068, v53
	v_add_u32_e32 v52, 0x8080, v53
	v_add_u32_e32 v54, 0x8088, v53
	v_add_u32_e32 v56, 0xa0a0, v53
	v_add_u32_e32 v58, 0xa0a8, v53
	v_add_u32_e32 v65, 0xc0c0, v53
	v_add_u32_e32 v66, 0xc0c8, v53
	v_add_u32_e32 v67, 0xe0e0, v53
	v_add_u32_e32 v68, 0xe0e8, v53
	v_ashrrev_i32_e32 v49, 31, v48
	v_lshlrev_b64 v[48:49], 10, v[48:49]
	s_ashr_i32 s93, s92, 31
	v_lshl_add_u64 v[48:49], s[90:91], 0, v[48:49]
	s_add_i32 s26, s26, s88
	s_add_i32 s39, s39, s5
	v_lshl_add_u64 v[48:49], s[92:93], 1, v[48:49]
	s_cmp_lt_i32 s26, 16
	v_lshl_add_u64 v[48:49], v[48:49], 0, v[34:35]
	s_waitcnt vmcnt(7)
	ds_write2_b32 v53, v2, v3 offset1:1
	ds_write2_b32 v53, v4, v5 offset0:2 offset1:3
	s_waitcnt vmcnt(6)
	ds_write2_b32 v41, v6, v7 offset1:1
	ds_write2_b32 v42, v8, v9 offset1:1
	s_waitcnt vmcnt(5)
	ds_write2_b32 v44, v10, v11 offset1:1
	ds_write2_b32 v46, v12, v13 offset1:1
	s_waitcnt vmcnt(4)
	ds_write2_b32 v50, v14, v15 offset1:1
	ds_write2_b32 v51, v16, v17 offset1:1
	s_waitcnt vmcnt(3)
	ds_write2_b32 v52, v18, v19 offset1:1
	ds_write2_b32 v54, v20, v21 offset1:1
	s_waitcnt vmcnt(2)
	ds_write2_b32 v56, v22, v23 offset1:1
	ds_write2_b32 v58, v24, v25 offset1:1
	s_waitcnt vmcnt(1)
	ds_write2_b32 v65, v26, v27 offset1:1
	ds_write2_b32 v66, v28, v29 offset1:1
	s_waitcnt vmcnt(0)
	ds_write2_b32 v67, v30, v31 offset1:1
	ds_write2_b32 v68, v32, v33 offset1:1
	s_waitcnt lgkmcnt(0)
	s_barrier
	ds_read_b32 v2, v57
	ds_read_b32 v3, v57 offset:1028
	ds_read_b32 v4, v57 offset:2056
	ds_read_b32 v5, v57 offset:3084
	ds_read_b32 v6, v57 offset:4112
	ds_read_b32 v7, v57 offset:5140
	ds_read_b32 v8, v57 offset:6168
	ds_read_b32 v9, v57 offset:7196
	ds_read_b32 v10, v57 offset:8224
	ds_read_b32 v11, v57 offset:9252
	ds_read_b32 v12, v57 offset:10280
	ds_read_b32 v13, v57 offset:11308
	ds_read_b32 v14, v57 offset:12336
	ds_read_b32 v15, v57 offset:13364
	ds_read_b32 v16, v57 offset:14392
	ds_read_b32 v17, v57 offset:15420
	ds_read_b32 v18, v57 offset:16448
	ds_read_b32 v19, v57 offset:17476
	ds_read_b32 v20, v57 offset:18504
	ds_read_b32 v21, v57 offset:19532
	ds_read_b32 v22, v57 offset:20560
	ds_read_b32 v23, v57 offset:21588
	ds_read_b32 v24, v57 offset:22616
	ds_read_b32 v25, v57 offset:23644
	ds_read_b32 v26, v57 offset:24672
	ds_read_b32 v27, v57 offset:25700
	ds_read_b32 v28, v57 offset:26728
	ds_read_b32 v29, v57 offset:27756
	ds_read_b32 v30, v57 offset:28784
	ds_read_b32 v31, v57 offset:29812
	ds_read_b32 v32, v57 offset:30840
	ds_read_b32 v33, v57 offset:31868
	s_waitcnt lgkmcnt(14)
	v_cvt_pk_bf16_f32 v2, v2, v3
	v_cvt_pk_bf16_f32 v3, v4, v5
	v_cvt_pk_bf16_f32 v4, v6, v7
	v_cvt_pk_bf16_f32 v5, v8, v9
	v_cvt_pk_bf16_f32 v6, v10, v11
	v_cvt_pk_bf16_f32 v7, v12, v13
	v_cvt_pk_bf16_f32 v8, v14, v15
	v_cvt_pk_bf16_f32 v9, v16, v17
	v_cvt_pk_bf16_f32 v10, v18, v19
	s_waitcnt lgkmcnt(12)
	v_cvt_pk_bf16_f32 v11, v20, v21
	s_waitcnt lgkmcnt(10)
	v_cvt_pk_bf16_f32 v12, v22, v23
	s_waitcnt lgkmcnt(8)
	v_cvt_pk_bf16_f32 v13, v24, v25
	s_waitcnt lgkmcnt(6)
	v_cvt_pk_bf16_f32 v14, v26, v27
	s_waitcnt lgkmcnt(4)
	v_cvt_pk_bf16_f32 v15, v28, v29
	s_waitcnt lgkmcnt(2)
	v_cvt_pk_bf16_f32 v16, v30, v31
	s_waitcnt lgkmcnt(0)
	v_cvt_pk_bf16_f32 v17, v32, v33
	global_store_dwordx4 v[48:49], v[2:5], off nt
	global_store_dwordx4 v[48:49], v[6:9], off offset:16 nt
	global_store_dwordx4 v[48:49], v[10:13], off offset:32 nt
	global_store_dwordx4 v[48:49], v[14:17], off offset:48 nt
	s_barrier
	s_cbranch_scc1 .LBB0_58

; #define LAS __attribute__((address_space(3)))
; __device__ __forceinline__ unsigned cvt_pk_bf16(float lo, float hi) { const f32x2 v = {lo, hi}; return __builtin_bit_cast(unsigned, __builtin_convertvector(v, bfx2_t)); }
; __device__ __forceinline__ void convT_tile(const float* src, int ldsrc, const float* sc, bf16_t* dst, int dstld, int k0, int n0, int swiglu, LAS float* t) {
;     const int tid = threadIdx.x;
;     { const int r = tid >> 6, c4 = (tid & 63) * 4;
;       int ncol = n0 + c4; if (swiglu) { const int blk = n0 >> 8; ncol = (c4 < 128) ? (128 * blk + c4) : (FF + 128 * blk + (c4 - 128)); }
;       f32x4 v[8]; float sv[8];
; #pragma unroll
;       for (int i = 0; i < 8; ++i) { const int rr = r + 8 * i; v[i] = *(const f32x4*)(src + (size_t)(k0 + rr) * ldsrc + ncol); sv[i] = sc ? sc[k0 + rr] : 1.0f; }
; #pragma unroll
;       for (int i = 0; i < 8; ++i) { const int rr = r + 8 * i; t[rr * 257 + c4 + 0] = v[i][0] * sv[i]; t[rr * 257 + c4 + 1] = v[i][1] * sv[i]; t[rr * 257 + c4 + 2] = v[i][2] * sv[i]; t[rr * 257 + c4 + 3] = v[i][3] * sv[i]; } }
;     __syncthreads();
;     { const int nn = tid >> 1, kh = (tid & 1) * 32;
; #pragma unroll
;       for (int q = 0; q < 4; ++q) { float v[8];
; #pragma unroll
;           for (int j = 0; j < 8; ++j) v[j] = t[(kh + q * 8 + j) * 257 + nn];
;           u32x4 w; w.x = cvt_pk_bf16(v[0], v[1]); w.y = cvt_pk_bf16(v[2], v[3]); w.z = cvt_pk_bf16(v[4], v[5]); w.w = cvt_pk_bf16(v[6], v[7]);
;           *(u32x4*)(dst + (size_t)(n0 + nn) * dstld + k0 + kh + q * 8) = w; } }
;     __syncthreads();
; }
.LBB0_61:
	s_ashr_i32 s80, s26, 31
	s_lshr_b32 s80, s80, 29
	s_add_i32 s80, s26, s80
	s_ashr_i32 s80, s80, 3
	s_lshl_b32 s81, s80, 9
	s_lshl_b32 s80, s80, 8
	s_sub_i32 s92, s39, s81
	v_or_b32_e32 v2, s80, v45
	v_add_u32_e32 v4, s92, v37
	v_ashrrev_i32_e32 v3, 31, v2
	v_lshl_add_u64 v[6:7], v[2:3], 2, s[0:1]
	v_add_u32_e32 v2, 8, v4
	v_add_u32_e32 v8, 16, v4
	v_add_u32_e32 v10, 24, v4
	v_add_u32_e32 v12, 32, v4
	v_add_u32_e32 v14, 40, v4
	v_add_u32_e32 v16, 48, v4
	v_add_u32_e32 v18, 56, v4
	v_ashrrev_i32_e32 v5, 31, v4
	v_ashrrev_i32_e32 v3, 31, v2
	v_ashrrev_i32_e32 v9, 31, v8
	v_ashrrev_i32_e32 v11, 31, v10
	v_ashrrev_i32_e32 v13, 31, v12
	v_ashrrev_i32_e32 v15, 31, v14
	v_ashrrev_i32_e32 v17, 31, v16
	v_ashrrev_i32_e32 v19, 31, v18
	v_lshlrev_b64 v[4:5], 12, v[4:5]
	v_lshlrev_b64 v[20:21], 12, v[2:3]
	v_lshlrev_b64 v[8:9], 12, v[8:9]
	v_lshlrev_b64 v[10:11], 12, v[10:11]
	v_lshlrev_b64 v[12:13], 12, v[12:13]
	v_lshlrev_b64 v[14:15], 12, v[14:15]
	v_lshlrev_b64 v[16:17], 12, v[16:17]
	v_lshlrev_b64 v[18:19], 12, v[18:19]
	v_lshl_add_u64 v[4:5], v[6:7], 0, v[4:5]
	v_lshl_add_u64 v[20:21], v[6:7], 0, v[20:21]
	v_lshl_add_u64 v[22:23], v[6:7], 0, v[8:9]
	v_lshl_add_u64 v[24:25], v[6:7], 0, v[10:11]
	v_lshl_add_u64 v[26:27], v[6:7], 0, v[12:13]
	v_lshl_add_u64 v[28:29], v[6:7], 0, v[14:15]
	v_lshl_add_u64 v[30:31], v[6:7], 0, v[16:17]
	v_lshl_add_u64 v[32:33], v[6:7], 0, v[18:19]
	global_load_dwordx4 v[2:5], v[4:5], off nt
	s_nop 0
	global_load_dwordx4 v[6:9], v[20:21], off nt
	global_load_dwordx4 v[10:13], v[22:23], off nt
	global_load_dwordx4 v[14:17], v[24:25], off nt
	s_nop 0
	global_load_dwordx4 v[18:21], v[26:27], off nt
	global_load_dwordx4 v[22:25], v[28:29], off nt
	s_nop 0
	global_load_dwordx4 v[26:29], v[30:31], off nt
	s_nop 0
	global_load_dwordx4 v[30:33], v[32:33], off nt
	v_add_u32_e32 v48, s80, v55
	v_add_u32_e32 v41, 0x2020, v53
	v_add_u32_e32 v42, 0x2028, v53
	v_add_u32_e32 v44, 0x4040, v53
	v_add_u32_e32 v46, 0x4048, v53
	v_add_u32_e32 v50, 0x6060, v53
	v_add_u32_e32 v51, 0x6068, v53
	v_add_u32_e32 v52, 0x8080, v53
	v_add_u32_e32 v54, 0x8088, v53
	v_add_u32_e32 v56, 0xa0a0, v53
	v_add_u32_e32 v58, 0xa0a8, v53
	v_add_u32_e32 v65, 0xc0c0, v53
	v_add_u32_e32 v66, 0xc0c8, v53
	v_add_u32_e32 v67, 0xe0e0, v53
	v_add_u32_e32 v68, 0xe0e8, v53
	v_ashrrev_i32_e32 v49, 31, v48
	v_lshlrev_b64 v[48:49], 11, v[48:49]
	s_ashr_i32 s93, s92, 31
	v_lshl_add_u64 v[48:49], s[90:91], 0, v[48:49]
	s_add_i32 s26, s26, s88
	s_add_i32 s39, s39, s5
	v_lshl_add_u64 v[48:49], s[92:93], 1, v[48:49]
	s_cmp_lt_i32 s26, 32
	v_lshl_add_u64 v[48:49], v[48:49], 0, v[34:35]
	s_waitcnt vmcnt(7)
	ds_write2_b32 v53, v2, v3 offset1:1
	ds_write2_b32 v53, v4, v5 offset0:2 offset1:3
	s_waitcnt vmcnt(6)
	ds_write2_b32 v41, v6, v7 offset1:1
	ds_write2_b32 v42, v8, v9 offset1:1
	s_waitcnt vmcnt(5)
	ds_write2_b32 v44, v10, v11 offset1:1
	ds_write2_b32 v46, v12, v13 offset1:1
	s_waitcnt vmcnt(4)
	ds_write2_b32 v50, v14, v15 offset1:1
	ds_write2_b32 v51, v16, v17 offset1:1
	s_waitcnt vmcnt(3)
	ds_write2_b32 v52, v18, v19 offset1:1
	ds_write2_b32 v54, v20, v21 offset1:1
	s_waitcnt vmcnt(2)
	ds_write2_b32 v56, v22, v23 offset1:1
	ds_write2_b32 v58, v24, v25 offset1:1
	s_waitcnt vmcnt(1)
	ds_write2_b32 v65, v26, v27 offset1:1
	ds_write2_b32 v66, v28, v29 offset1:1
	s_waitcnt vmcnt(0)
	ds_write2_b32 v67, v30, v31 offset1:1
	ds_write2_b32 v68, v32, v33 offset1:1
	s_waitcnt lgkmcnt(0)
	s_barrier
	ds_read_b32 v2, v57
	ds_read_b32 v3, v57 offset:1028
	ds_read_b32 v4, v57 offset:2056
	ds_read_b32 v5, v57 offset:3084
	ds_read_b32 v6, v57 offset:4112
	ds_read_b32 v7, v57 offset:5140
	ds_read_b32 v8, v57 offset:6168
	ds_read_b32 v9, v57 offset:7196
	ds_read_b32 v10, v57 offset:8224
	ds_read_b32 v11, v57 offset:9252
	ds_read_b32 v12, v57 offset:10280
	ds_read_b32 v13, v57 offset:11308
	ds_read_b32 v14, v57 offset:12336
	ds_read_b32 v15, v57 offset:13364
	ds_read_b32 v16, v57 offset:14392
	ds_read_b32 v17, v57 offset:15420
	ds_read_b32 v18, v57 offset:16448
	ds_read_b32 v19, v57 offset:17476
	ds_read_b32 v20, v57 offset:18504
	ds_read_b32 v21, v57 offset:19532
	ds_read_b32 v22, v57 offset:20560
	ds_read_b32 v23, v57 offset:21588
	ds_read_b32 v24, v57 offset:22616
	ds_read_b32 v25, v57 offset:23644
	ds_read_b32 v26, v57 offset:24672
	ds_read_b32 v27, v57 offset:25700
	ds_read_b32 v28, v57 offset:26728
	ds_read_b32 v29, v57 offset:27756
	ds_read_b32 v30, v57 offset:28784
	ds_read_b32 v31, v57 offset:29812
	ds_read_b32 v32, v57 offset:30840
	ds_read_b32 v33, v57 offset:31868
	s_waitcnt lgkmcnt(14)
	v_cvt_pk_bf16_f32 v2, v2, v3
	v_cvt_pk_bf16_f32 v3, v4, v5
	v_cvt_pk_bf16_f32 v4, v6, v7
	v_cvt_pk_bf16_f32 v5, v8, v9
	v_cvt_pk_bf16_f32 v6, v10, v11
	v_cvt_pk_bf16_f32 v7, v12, v13
	v_cvt_pk_bf16_f32 v8, v14, v15
	v_cvt_pk_bf16_f32 v9, v16, v17
	v_cvt_pk_bf16_f32 v10, v18, v19
	s_waitcnt lgkmcnt(12)
	v_cvt_pk_bf16_f32 v11, v20, v21
	s_waitcnt lgkmcnt(10)
	v_cvt_pk_bf16_f32 v12, v22, v23
	s_waitcnt lgkmcnt(8)
	v_cvt_pk_bf16_f32 v13, v24, v25
	s_waitcnt lgkmcnt(6)
	v_cvt_pk_bf16_f32 v14, v26, v27
	s_waitcnt lgkmcnt(4)
	v_cvt_pk_bf16_f32 v15, v28, v29
	s_waitcnt lgkmcnt(2)
	v_cvt_pk_bf16_f32 v16, v30, v31
	s_waitcnt lgkmcnt(0)
	v_cvt_pk_bf16_f32 v17, v32, v33
	global_store_dwordx4 v[48:49], v[2:5], off nt
	global_store_dwordx4 v[48:49], v[6:9], off offset:16 nt
	global_store_dwordx4 v[48:49], v[10:13], off offset:32 nt
	global_store_dwordx4 v[48:49], v[14:17], off offset:48 nt
	s_barrier
	s_cbranch_scc1 .LBB0_61

; __device__ __forceinline__ unsigned cvt_pk_bf16(float lo, float hi) { const f32x2 v = {lo, hi}; return __builtin_bit_cast(unsigned, __builtin_convertvector(v, bfx2_t)); }
; __device__ __forceinline__ void conv_poolout(const float* pw, const float* pscale, const float* wout, bf16_t* dst, LAS float* t, int& base) {
;     ...
;     for (int idx = first; idx < ntiles; idx += G) {
;         const int k0 = (idx & 7) * 64, n0 = (idx >> 3) * 64;
;         const int tn = tid & 63, tk = tid >> 6; const int kb = k0 + tk * 8; const int gi = kb >> 7, kk0 = kb & 127;
;         float a[8];
; #pragma unroll
;         for (int i = 0; i < 8; ++i) a[i] = 0.f;
;         const float* pwg = pw + (size_t)gi * 128 * 128 + (size_t)kk0 * 128;
;         for (int m = 0; m < 128; ++m) {
;             const float w = wout[(size_t)(512 + gi * 128 + m) * DM + n0 + tn] * pscale[gi * 128 + m];
; #pragma unroll
;             for (int i = 0; i < 8; ++i) a[i] += pwg[i * 128 + m] * w;
;         }
; #pragma unroll
;         for (int i = 0; i < 8; ++i) t[(tk * 8 + i) * 65 + tn] = a[i];
;         __syncthreads();
;         { const int nn = tid >> 3, k8 = (tid & 7) * 8; float v[8];
; #pragma unroll
;           for (int j = 0; j < 8; ++j) v[j] = t[(k8 + j) * 65 + nn];
;           u32x4 w; w.x = cvt_pk_bf16(v[0], v[1]); w.y = cvt_pk_bf16(v[2], v[3]); w.z = cvt_pk_bf16(v[4], v[5]); w.w = cvt_pk_bf16(v[6], v[7]);
;           *(u32x4*)(dst + (size_t)(n0 + nn) * DM + 512 + k0 + k8) = w; }
;         __syncthreads();
;     }
.LBB0_65:
	v_lshl_add_u64 v[82:83], v[2:3], 0, s[92:93]
	s_mov_b32 s0, 0x202000
	v_add_co_u32_e64 v86, s[0:1], s0, v82
	s_mov_b32 s26, 0x203000
	s_nop 0
	v_addc_co_u32_e64 v87, s[0:1], 0, v83, s[0:1]
	global_load_dwordx4 v[18:21], v[6:7], off offset:-12
	global_load_dwordx4 v[22:25], v[6:7], off offset:500
	global_load_dwordx4 v[26:29], v[6:7], off offset:1012
	global_load_dwordx4 v[30:33], v[6:7], off offset:1524
	global_load_dwordx4 v[48:51], v[6:7], off offset:2036
	global_load_dwordx4 v[66:69], v[6:7], off offset:2548
	global_load_dwordx4 v[70:73], v[6:7], off offset:3060
	global_load_dwordx4 v[74:77], v[6:7], off offset:3572
	global_load_dwordx4 v[78:81], v[4:5], off
	v_add_co_u32_e32 v84, vcc, 0x200000, v82
	v_add_co_u32_e64 v88, s[0:1], s26, v82
	s_nop 0
	v_addc_co_u32_e32 v85, vcc, 0, v83, vcc
	v_addc_co_u32_e64 v89, s[0:1], 0, v83, s[0:1]
	global_load_dword v17, v[86:87], off offset:-4096
	global_load_dword v41, v[86:87], off
	global_load_dword v44, v[84:85], off
	global_load_dword v42, v[88:89], off
	s_add_u32 s92, s92, 0x4000
	s_addc_u32 s93, s93, 0
	v_lshl_add_u64 v[4:5], v[4:5], 0, 16
	v_lshl_add_u64 v[6:7], v[6:7], 0, 16
	s_cmp_eq_u32 s92, 0x80000
	s_waitcnt vmcnt(12)
	v_mov_b32_e32 v82, v18
	s_waitcnt vmcnt(11)
	v_mov_b32_e32 v83, v22
	s_waitcnt vmcnt(10)
	v_mov_b32_e32 v84, v26
	s_waitcnt vmcnt(9)
	v_mov_b32_e32 v85, v30
	s_waitcnt vmcnt(8)
	v_mov_b32_e32 v86, v48
	s_waitcnt vmcnt(7)
	v_mov_b32_e32 v87, v66
	s_waitcnt vmcnt(6)
	v_mov_b32_e32 v88, v70
	s_waitcnt vmcnt(5)
	v_mov_b32_e32 v89, v74
	v_mov_b32_e32 v22, v19
	v_mov_b32_e32 v30, v27
	v_mov_b32_e32 v66, v49
	v_mov_b32_e32 v74, v71
	v_mov_b32_e32 v18, v20
	v_mov_b32_e32 v19, v24
	s_waitcnt vmcnt(3)
	v_mul_f32_e32 v20, v17, v79
	v_mov_b32_e32 v26, v28
	s_waitcnt vmcnt(1)
	v_mul_f32_e32 v44, v44, v78
	v_pk_fma_f32 v[10:11], v[44:45], v[82:83], v[10:11] op_sel_hi:[0,1,1]
	v_pk_fma_f32 v[14:15], v[44:45], v[84:85], v[14:15] op_sel_hi:[0,1,1]
	v_pk_fma_f32 v[12:13], v[44:45], v[86:87], v[12:13] op_sel_hi:[0,1,1]
	v_pk_fma_f32 v[8:9], v[44:45], v[88:89], v[8:9] op_sel_hi:[0,1,1]
	v_mov_b32_e32 v27, v32
	v_mov_b32_e32 v48, v50
	v_mov_b32_e32 v49, v68
	v_mov_b32_e32 v70, v72
	v_mov_b32_e32 v71, v76
	v_mul_f32_e32 v28, v41, v80
	v_pk_fma_f32 v[10:11], v[20:21], v[22:23], v[10:11] op_sel_hi:[0,1,1]
	v_pk_fma_f32 v[14:15], v[20:21], v[30:31], v[14:15] op_sel_hi:[0,1,1]
	v_pk_fma_f32 v[12:13], v[20:21], v[66:67], v[12:13] op_sel_hi:[0,1,1]
	v_pk_fma_f32 v[8:9], v[20:21], v[74:75], v[8:9] op_sel_hi:[0,1,1]
	v_mov_b32_e32 v24, v21
	v_mov_b32_e32 v32, v29
	v_mov_b32_e32 v68, v51
	v_mov_b32_e32 v76, v73
	s_waitcnt vmcnt(0)
	v_mul_f32_e32 v42, v42, v81
	v_pk_fma_f32 v[10:11], v[28:29], v[18:19], v[10:11] op_sel_hi:[0,1,1]
	v_pk_fma_f32 v[14:15], v[28:29], v[26:27], v[14:15] op_sel_hi:[0,1,1]
	v_pk_fma_f32 v[12:13], v[28:29], v[48:49], v[12:13] op_sel_hi:[0,1,1]
	v_pk_fma_f32 v[8:9], v[28:29], v[70:71], v[8:9] op_sel_hi:[0,1,1]
	v_pk_fma_f32 v[10:11], v[42:43], v[24:25], v[10:11] op_sel_hi:[0,1,1]
	v_pk_fma_f32 v[14:15], v[42:43], v[32:33], v[14:15] op_sel_hi:[0,1,1]
	v_pk_fma_f32 v[12:13], v[42:43], v[68:69], v[12:13] op_sel_hi:[0,1,1]
	v_pk_fma_f32 v[8:9], v[42:43], v[76:77], v[8:9] op_sel_hi:[0,1,1]
	s_cbranch_scc0 .LBB0_65
	v_add_u32_e32 v2, 0x400, v62
	ds_write2_b32 v62, v10, v11 offset1:65
	ds_write2_b32 v62, v14, v15 offset0:130 offset1:195
	ds_write2_b32 v2, v12, v13 offset0:4 offset1:69
	ds_write_b32 v62, v8 offset:1560
	ds_write_b32 v63, v9
	s_waitcnt lgkmcnt(0)
	s_barrier
	ds_read2_b32 v[2:3], v64 offset1:65
	ds_read2_b32 v[4:5], v64 offset0:130 offset1:195
	v_add_u32_e32 v8, 0x400, v64
	ds_read2_b32 v[6:7], v8 offset0:4 offset1:69
	ds_read2_b32 v[8:9], v8 offset0:134 offset1:199
	s_lshl_b32 s0, s39, 3
	s_andn2_b32 s0, s0, 63
	s_waitcnt lgkmcnt(3)
	v_cvt_pk_bf16_f32 v2, v2, v3
	s_waitcnt lgkmcnt(2)
	v_cvt_pk_bf16_f32 v3, v4, v5
	s_waitcnt lgkmcnt(1)
	v_cvt_pk_bf16_f32 v4, v6, v7
	v_add_u32_e32 v6, s0, v59
	v_ashrrev_i32_e32 v7, 31, v6
	v_lshlrev_b64 v[6:7], 11, v[6:7]
	s_lshl_b32 s0, s39, 7
	v_lshl_add_u64 v[6:7], s[90:91], 0, v[6:7]
	s_and_b32 s26, s0, 0x380
	v_lshl_add_u64 v[6:7], v[6:7], 0, s[26:27]
	v_mov_b32_e32 v41, v35
	s_add_i32 s39, s39, s88
	s_add_i32 s94, s94, s5
	s_waitcnt lgkmcnt(0)
	v_cvt_pk_bf16_f32 v5, v8, v9
	v_lshl_add_u64 v[6:7], v[6:7], 0, v[40:41]
	s_cmpk_gt_i32 s39, 0x7f
	v_add_u32_e32 v16, v16, v164
	global_store_dwordx4 v[6:7], v[2:5], off offset:1024 nt
	s_barrier
	s_cbranch_scc0 .LBB0_64

; #define LAS __attribute__((address_space(3)))
; __device__ __forceinline__ unsigned cvt_pk_bf16(float lo, float hi) { const f32x2 v = {lo, hi}; return __builtin_bit_cast(unsigned, __builtin_convertvector(v, bfx2_t)); }
; __device__ __forceinline__ void convT_tile(const float* src, int ldsrc, const float* sc, bf16_t* dst, int dstld, int k0, int n0, int swiglu, LAS float* t) {
;     const int tid = threadIdx.x;
;     { const int r = tid >> 6, c4 = (tid & 63) * 4;
;       int ncol = n0 + c4; if (swiglu) { const int blk = n0 >> 8; ncol = (c4 < 128) ? (128 * blk + c4) : (FF + 128 * blk + (c4 - 128)); }
;       f32x4 v[8]; float sv[8];
; #pragma unroll
;       for (int i = 0; i < 8; ++i) { const int rr = r + 8 * i; v[i] = *(const f32x4*)(src + (size_t)(k0 + rr) * ldsrc + ncol); sv[i] = sc ? sc[k0 + rr] : 1.0f; }
; #pragma unroll
;       for (int i = 0; i < 8; ++i) { const int rr = r + 8 * i; t[rr * 257 + c4 + 0] = v[i][0] * sv[i]; t[rr * 257 + c4 + 1] = v[i][1] * sv[i]; t[rr * 257 + c4 + 2] = v[i][2] * sv[i]; t[rr * 257 + c4 + 3] = v[i][3] * sv[i]; } }
;     __syncthreads();
;     { const int nn = tid >> 1, kh = (tid & 1) * 32;
; #pragma unroll
;       for (int q = 0; q < 4; ++q) { float v[8];
; #pragma unroll
;           for (int j = 0; j < 8; ++j) v[j] = t[(kh + q * 8 + j) * 257 + nn];
;           u32x4 w; w.x = cvt_pk_bf16(v[0], v[1]); w.y = cvt_pk_bf16(v[2], v[3]); w.z = cvt_pk_bf16(v[4], v[5]); w.w = cvt_pk_bf16(v[6], v[7]);
;           *(u32x4*)(dst + (size_t)(n0 + nn) * dstld + k0 + kh + q * 8) = w; } }
;     __syncthreads();
; }
.LBB0_69:
	s_waitcnt vmcnt(7)
	v_pk_mul_f32 v[2:3], v[2:3], v[46:47] op_sel_hi:[1,0]
	ds_write2_b32 v53, v2, v3 offset1:1
	v_pk_mul_f32 v[2:3], v[4:5], v[46:47] op_sel_hi:[1,0]
	ds_write2_b32 v53, v2, v3 offset0:2 offset1:3
	s_waitcnt vmcnt(6)
	v_pk_mul_f32 v[2:3], v[6:7], v[42:43] op_sel_hi:[1,0]
	v_add_u32_e32 v4, 0x2020, v53
	ds_write2_b32 v4, v2, v3 offset1:1
	v_pk_mul_f32 v[2:3], v[8:9], v[42:43] op_sel_hi:[1,0]
	v_add_u32_e32 v4, 0x2028, v53
	ds_write2_b32 v4, v2, v3 offset1:1
	s_waitcnt vmcnt(5)
	v_pk_mul_f32 v[2:3], v[10:11], v[52:53] op_sel_hi:[1,0]
	v_add_u32_e32 v4, 0x4040, v53
	ds_write2_b32 v4, v2, v3 offset1:1
	v_pk_mul_f32 v[2:3], v[12:13], v[52:53] op_sel_hi:[1,0]
	v_add_u32_e32 v4, 0x4048, v53
	ds_write2_b32 v4, v2, v3 offset1:1
	s_waitcnt vmcnt(4)
	v_pk_mul_f32 v[2:3], v[14:15], v[44:45] op_sel_hi:[1,0]
	v_add_u32_e32 v4, 0x6060, v53
	ds_write2_b32 v4, v2, v3 offset1:1
	v_pk_mul_f32 v[2:3], v[16:17], v[44:45] op_sel_hi:[1,0]
	v_add_u32_e32 v4, 0x6068, v53
	ds_write2_b32 v4, v2, v3 offset1:1
	s_waitcnt vmcnt(3)
	v_pk_mul_f32 v[2:3], v[18:19], v[56:57] op_sel_hi:[1,0]
	v_add_u32_e32 v4, 0x8080, v53
	ds_write2_b32 v4, v2, v3 offset1:1
	v_pk_mul_f32 v[2:3], v[20:21], v[56:57] op_sel_hi:[1,0]
	v_add_u32_e32 v4, 0x8088, v53
	ds_write2_b32 v4, v2, v3 offset1:1
	s_waitcnt vmcnt(2)
	v_pk_mul_f32 v[2:3], v[22:23], v[48:49] op_sel_hi:[1,0]
	v_add_u32_e32 v4, 0xa0a0, v53
	ds_write2_b32 v4, v2, v3 offset1:1
	v_pk_mul_f32 v[2:3], v[24:25], v[48:49] op_sel_hi:[1,0]
	v_add_u32_e32 v4, 0xa0a8, v53
	ds_write2_b32 v4, v2, v3 offset1:1
	s_waitcnt vmcnt(1)
	v_pk_mul_f32 v[2:3], v[26:27], v[58:59] op_sel_hi:[1,0]
	v_add_u32_e32 v4, 0xc0c0, v53
	ds_write2_b32 v4, v2, v3 offset1:1
	v_pk_mul_f32 v[2:3], v[28:29], v[58:59] op_sel_hi:[1,0]
	v_add_u32_e32 v4, 0xc0c8, v53
	ds_write2_b32 v4, v2, v3 offset1:1
	s_waitcnt vmcnt(0)
	v_pk_mul_f32 v[2:3], v[30:31], v[54:55] op_sel_hi:[1,0]
	v_add_u32_e32 v4, 0xe0e0, v53
	ds_write2_b32 v4, v2, v3 offset1:1
	v_pk_mul_f32 v[2:3], v[32:33], v[54:55] op_sel_hi:[1,0]
	v_add_u32_e32 v4, 0xe0e8, v53
	ds_write2_b32 v4, v2, v3 offset1:1
	s_waitcnt lgkmcnt(0)
	s_barrier
	v_lshl_add_u32 v2, s80, 8, v55
	ds_read_b32 v4, v57
	ds_read_b32 v5, v57 offset:1028
	ds_read_b32 v8, v57 offset:2056
	ds_read_b32 v9, v57 offset:3084
	ds_read_b32 v10, v57 offset:4112
	ds_read_b32 v11, v57 offset:5140
	ds_read_b32 v12, v57 offset:6168
	ds_read_b32 v13, v57 offset:7196
	v_ashrrev_i32_e32 v3, 31, v2
	s_add_i32 s0, s39, s0
	v_lshlrev_b64 v[2:3], 11, v[2:3]
	v_lshl_add_u64 v[2:3], s[92:93], 0, v[2:3]
	s_ashr_i32 s1, s0, 31
	v_lshl_add_u64 v[2:3], s[0:1], 1, v[2:3]
	v_lshl_add_u64 v[6:7], v[2:3], 0, v[34:35]
	s_waitcnt lgkmcnt(6)
	v_cvt_pk_bf16_f32 v2, v4, v5
	s_waitcnt lgkmcnt(4)
	v_cvt_pk_bf16_f32 v3, v8, v9
	s_waitcnt lgkmcnt(2)
	v_cvt_pk_bf16_f32 v4, v10, v11
	s_waitcnt lgkmcnt(0)
	v_cvt_pk_bf16_f32 v5, v12, v13
	ds_read_b32 v8, v57 offset:8224
	ds_read_b32 v9, v57 offset:9252
	ds_read_b32 v10, v57 offset:10280
	ds_read_b32 v11, v57 offset:11308
	ds_read_b32 v12, v57 offset:12336
	ds_read_b32 v13, v57 offset:13364
	ds_read_b32 v14, v57 offset:14392
	ds_read_b32 v15, v57 offset:15420
	global_store_dwordx4 v[6:7], v[2:5], off nt
	s_add_i32 s26, s26, s88
	s_add_i32 s39, s39, s5
	s_waitcnt lgkmcnt(6)
	v_cvt_pk_bf16_f32 v2, v8, v9
	s_waitcnt lgkmcnt(4)
	v_cvt_pk_bf16_f32 v3, v10, v11
	s_waitcnt lgkmcnt(2)
	v_cvt_pk_bf16_f32 v4, v12, v13
	s_waitcnt lgkmcnt(0)
	v_cvt_pk_bf16_f32 v5, v14, v15
	ds_read_b32 v8, v57 offset:16448
	ds_read_b32 v9, v57 offset:17476
	ds_read_b32 v10, v57 offset:18504
	ds_read_b32 v11, v57 offset:19532
	ds_read_b32 v12, v57 offset:20560
	ds_read_b32 v13, v57 offset:21588
	ds_read_b32 v14, v57 offset:22616
	ds_read_b32 v15, v57 offset:23644
	global_store_dwordx4 v[6:7], v[2:5], off offset:16 nt
	s_cmpk_lt_i32 s26, 0x160
	s_waitcnt lgkmcnt(6)
	v_cvt_pk_bf16_f32 v2, v8, v9
	s_waitcnt lgkmcnt(4)
	v_cvt_pk_bf16_f32 v3, v10, v11
	s_waitcnt lgkmcnt(2)
	v_cvt_pk_bf16_f32 v4, v12, v13
	s_waitcnt lgkmcnt(0)
	v_cvt_pk_bf16_f32 v5, v14, v15
	ds_read_b32 v8, v57 offset:24672
	ds_read_b32 v9, v57 offset:25700
	ds_read_b32 v10, v57 offset:26728
	ds_read_b32 v11, v57 offset:27756
	ds_read_b32 v12, v57 offset:28784
	ds_read_b32 v13, v57 offset:29812
	ds_read_b32 v14, v57 offset:30840
	ds_read_b32 v15, v57 offset:31868
	global_store_dwordx4 v[6:7], v[2:5], off offset:32 nt
	s_waitcnt lgkmcnt(6)
	s_nop 0
	v_cvt_pk_bf16_f32 v2, v8, v9
	s_waitcnt lgkmcnt(4)
	v_cvt_pk_bf16_f32 v3, v10, v11
	s_waitcnt lgkmcnt(2)
	v_cvt_pk_bf16_f32 v4, v12, v13
	s_waitcnt lgkmcnt(0)
	v_cvt_pk_bf16_f32 v5, v14, v15
	global_store_dwordx4 v[6:7], v[2:5], off offset:48 nt
	s_barrier
	s_cbranch_scc0 .LBB0_86

; #define LAS __attribute__((address_space(3)))
; __device__ __forceinline__ unsigned cvt_pk_bf16(float lo, float hi) { const f32x2 v = {lo, hi}; return __builtin_bit_cast(unsigned, __builtin_convertvector(v, bfx2_t)); }
; __device__ __forceinline__ void convT_tile(const float* src, int ldsrc, const float* sc, bf16_t* dst, int dstld, int k0, int n0, int swiglu, LAS float* t) {
;     const int tid = threadIdx.x;
;     { const int r = tid >> 6, c4 = (tid & 63) * 4;
;       int ncol = n0 + c4; if (swiglu) { const int blk = n0 >> 8; ncol = (c4 < 128) ? (128 * blk + c4) : (FF + 128 * blk + (c4 - 128)); }
;       f32x4 v[8]; float sv[8];
; #pragma unroll
;       for (int i = 0; i < 8; ++i) { const int rr = r + 8 * i; v[i] = *(const f32x4*)(src + (size_t)(k0 + rr) * ldsrc + ncol); sv[i] = sc ? sc[k0 + rr] : 1.0f; }
; #pragma unroll
;       for (int i = 0; i < 8; ++i) { const int rr = r + 8 * i; t[rr * 257 + c4 + 0] = v[i][0] * sv[i]; t[rr * 257 + c4 + 1] = v[i][1] * sv[i]; t[rr * 257 + c4 + 2] = v[i][2] * sv[i]; t[rr * 257 + c4 + 3] = v[i][3] * sv[i]; } }
;     __syncthreads();
;     { const int nn = tid >> 1, kh = (tid & 1) * 32;
; #pragma unroll
;       for (int q = 0; q < 4; ++q) { float v[8];
; #pragma unroll
;           for (int j = 0; j < 8; ++j) v[j] = t[(kh + q * 8 + j) * 257 + nn];
;           u32x4 w; w.x = cvt_pk_bf16(v[0], v[1]); w.y = cvt_pk_bf16(v[2], v[3]); w.z = cvt_pk_bf16(v[4], v[5]); w.w = cvt_pk_bf16(v[6], v[7]);
;           *(u32x4*)(dst + (size_t)(n0 + nn) * dstld + k0 + kh + q * 8) = w; } }
;     __syncthreads();
; }
.LBB0_88:
	s_mul_hi_i32 s64, s26, 0x2e8ba2e9
	s_lshr_b32 s65, s64, 31
	s_ashr_i32 s64, s64, 3
	s_add_i32 s64, s64, s65
	s_mul_i32 s65, s64, 0xfffff500
	s_lshl_b32 s80, s64, 8
	s_add_i32 s64, s39, s65
	v_or_b32_e32 v2, s80, v45
	v_add_u32_e32 v4, s64, v37
	v_ashrrev_i32_e32 v3, 31, v2
	v_lshl_add_u64 v[6:7], v[2:3], 2, s[0:1]
	v_add_u32_e32 v2, 8, v4
	v_add_u32_e32 v8, 16, v4
	v_add_u32_e32 v10, 24, v4
	v_add_u32_e32 v12, 32, v4
	v_add_u32_e32 v14, 40, v4
	v_add_u32_e32 v16, 48, v4
	v_add_u32_e32 v18, 56, v4
	v_ashrrev_i32_e32 v5, 31, v4
	v_ashrrev_i32_e32 v3, 31, v2
	v_ashrrev_i32_e32 v9, 31, v8
	v_ashrrev_i32_e32 v11, 31, v10
	v_ashrrev_i32_e32 v13, 31, v12
	v_ashrrev_i32_e32 v15, 31, v14
	v_ashrrev_i32_e32 v17, 31, v16
	v_ashrrev_i32_e32 v19, 31, v18
	v_lshlrev_b64 v[4:5], 12, v[4:5]
	v_lshlrev_b64 v[20:21], 12, v[2:3]
	v_lshlrev_b64 v[8:9], 12, v[8:9]
	v_lshlrev_b64 v[10:11], 12, v[10:11]
	v_lshlrev_b64 v[12:13], 12, v[12:13]
	v_lshlrev_b64 v[14:15], 12, v[14:15]
	v_lshlrev_b64 v[16:17], 12, v[16:17]
	v_lshlrev_b64 v[18:19], 12, v[18:19]
	v_lshl_add_u64 v[4:5], v[6:7], 0, v[4:5]
	v_lshl_add_u64 v[20:21], v[6:7], 0, v[20:21]
	v_lshl_add_u64 v[22:23], v[6:7], 0, v[8:9]
	v_lshl_add_u64 v[24:25], v[6:7], 0, v[10:11]
	v_lshl_add_u64 v[26:27], v[6:7], 0, v[12:13]
	v_lshl_add_u64 v[28:29], v[6:7], 0, v[14:15]
	v_lshl_add_u64 v[30:31], v[6:7], 0, v[16:17]
	v_lshl_add_u64 v[32:33], v[6:7], 0, v[18:19]
	global_load_dwordx4 v[2:5], v[4:5], off nt
	s_nop 0
	global_load_dwordx4 v[6:9], v[20:21], off nt
	global_load_dwordx4 v[10:13], v[22:23], off nt
	global_load_dwordx4 v[14:17], v[24:25], off nt
	s_nop 0
	global_load_dwordx4 v[18:21], v[26:27], off nt
	global_load_dwordx4 v[22:25], v[28:29], off nt
	s_nop 0
	global_load_dwordx4 v[26:29], v[30:31], off nt
	s_nop 0
	global_load_dwordx4 v[30:33], v[32:33], off nt
	v_add_u32_e32 v41, 0x2020, v53
	v_add_u32_e32 v42, 0x2028, v53
	v_add_u32_e32 v44, 0x4040, v53
	v_add_u32_e32 v46, 0x4048, v53
	v_add_u32_e32 v50, 0x6060, v53
	v_add_u32_e32 v51, 0x6068, v53
	v_add_u32_e32 v52, 0x8080, v53
	v_add_u32_e32 v54, 0x8088, v53
	v_add_u32_e32 v56, 0xa0a0, v53
	v_add_u32_e32 v58, 0xa0a8, v53
	v_add_u32_e32 v65, 0xc0c0, v53
	v_add_u32_e32 v66, 0xc0c8, v53
	v_add_u32_e32 v67, 0xe0e0, v53
	v_add_u32_e32 v68, 0xe0e8, v53
	v_mov_b64_e32 v[48:49], s[46:47]
	v_add_u32_e32 v69, s80, v55
	v_mad_i64_i32 v[48:49], s[80:81], v69, s25, v[48:49]
	s_ashr_i32 s65, s64, 31
	s_add_i32 s26, s26, s88
	s_add_i32 s39, s39, s5
	v_lshl_add_u64 v[48:49], s[64:65], 1, v[48:49]
	s_cmpk_lt_i32 s26, 0xb0
	v_lshl_add_u64 v[48:49], v[48:49], 0, v[34:35]
	s_waitcnt vmcnt(7)
	ds_write2_b32 v53, v2, v3 offset1:1
	ds_write2_b32 v53, v4, v5 offset0:2 offset1:3
	s_waitcnt vmcnt(6)
	ds_write2_b32 v41, v6, v7 offset1:1
	ds_write2_b32 v42, v8, v9 offset1:1
	s_waitcnt vmcnt(5)
	ds_write2_b32 v44, v10, v11 offset1:1
	ds_write2_b32 v46, v12, v13 offset1:1
	s_waitcnt vmcnt(4)
	ds_write2_b32 v50, v14, v15 offset1:1
	ds_write2_b32 v51, v16, v17 offset1:1
	s_waitcnt vmcnt(3)
	ds_write2_b32 v52, v18, v19 offset1:1
	ds_write2_b32 v54, v20, v21 offset1:1
	s_waitcnt vmcnt(2)
	ds_write2_b32 v56, v22, v23 offset1:1
	ds_write2_b32 v58, v24, v25 offset1:1
	s_waitcnt vmcnt(1)
	ds_write2_b32 v65, v26, v27 offset1:1
	ds_write2_b32 v66, v28, v29 offset1:1
	s_waitcnt vmcnt(0)
	ds_write2_b32 v67, v30, v31 offset1:1
	ds_write2_b32 v68, v32, v33 offset1:1
	s_waitcnt lgkmcnt(0)
	s_barrier
	ds_read_b32 v2, v57
	ds_read_b32 v3, v57 offset:1028
	ds_read_b32 v4, v57 offset:2056
	ds_read_b32 v5, v57 offset:3084
	ds_read_b32 v6, v57 offset:4112
	ds_read_b32 v7, v57 offset:5140
	ds_read_b32 v8, v57 offset:6168
	ds_read_b32 v9, v57 offset:7196
	ds_read_b32 v10, v57 offset:8224
	ds_read_b32 v11, v57 offset:9252
	ds_read_b32 v12, v57 offset:10280
	ds_read_b32 v13, v57 offset:11308
	ds_read_b32 v14, v57 offset:12336
	ds_read_b32 v15, v57 offset:13364
	ds_read_b32 v16, v57 offset:14392
	ds_read_b32 v17, v57 offset:15420
	ds_read_b32 v18, v57 offset:16448
	ds_read_b32 v19, v57 offset:17476
	ds_read_b32 v20, v57 offset:18504
	ds_read_b32 v21, v57 offset:19532
	ds_read_b32 v22, v57 offset:20560
	ds_read_b32 v23, v57 offset:21588
	ds_read_b32 v24, v57 offset:22616
	ds_read_b32 v25, v57 offset:23644
	ds_read_b32 v26, v57 offset:24672
	ds_read_b32 v27, v57 offset:25700
	ds_read_b32 v28, v57 offset:26728
	ds_read_b32 v29, v57 offset:27756
	ds_read_b32 v30, v57 offset:28784
	ds_read_b32 v31, v57 offset:29812
	ds_read_b32 v32, v57 offset:30840
	ds_read_b32 v33, v57 offset:31868
	s_waitcnt lgkmcnt(14)
	v_cvt_pk_bf16_f32 v2, v2, v3
	v_cvt_pk_bf16_f32 v3, v4, v5
	v_cvt_pk_bf16_f32 v4, v6, v7
	v_cvt_pk_bf16_f32 v5, v8, v9
	v_cvt_pk_bf16_f32 v6, v10, v11
	v_cvt_pk_bf16_f32 v7, v12, v13
	v_cvt_pk_bf16_f32 v8, v14, v15
	v_cvt_pk_bf16_f32 v9, v16, v17
	v_cvt_pk_bf16_f32 v10, v18, v19
	s_waitcnt lgkmcnt(12)
	v_cvt_pk_bf16_f32 v11, v20, v21
	s_waitcnt lgkmcnt(10)
	v_cvt_pk_bf16_f32 v12, v22, v23
	s_waitcnt lgkmcnt(8)
	v_cvt_pk_bf16_f32 v13, v24, v25
	s_waitcnt lgkmcnt(6)
	v_cvt_pk_bf16_f32 v14, v26, v27
	s_waitcnt lgkmcnt(4)
	v_cvt_pk_bf16_f32 v15, v28, v29
	s_waitcnt lgkmcnt(2)
	v_cvt_pk_bf16_f32 v16, v30, v31
	s_waitcnt lgkmcnt(0)
	v_cvt_pk_bf16_f32 v17, v32, v33
	global_store_dwordx4 v[48:49], v[2:5], off nt
	global_store_dwordx4 v[48:49], v[6:9], off offset:16 nt
	global_store_dwordx4 v[48:49], v[10:13], off offset:32 nt
	global_store_dwordx4 v[48:49], v[14:17], off offset:48 nt
	s_barrier
	s_cbranch_scc1 .LBB0_88

; #define LAS __attribute__((address_space(3)))
; __device__ __forceinline__ unsigned cvt_pk_bf16(float lo, float hi) { const f32x2 v = {lo, hi}; return __builtin_bit_cast(unsigned, __builtin_convertvector(v, bfx2_t)); }
; __device__ __forceinline__ void convT_tile(const float* src, int ldsrc, const float* sc, bf16_t* dst, int dstld, int k0, int n0, int swiglu, LAS float* t) {
;     const int tid = threadIdx.x;
;     { const int r = tid >> 6, c4 = (tid & 63) * 4;
;       int ncol = n0 + c4; if (swiglu) { const int blk = n0 >> 8; ncol = (c4 < 128) ? (128 * blk + c4) : (FF + 128 * blk + (c4 - 128)); }
;       f32x4 v[8]; float sv[8];
; #pragma unroll
;       for (int i = 0; i < 8; ++i) { const int rr = r + 8 * i; v[i] = *(const f32x4*)(src + (size_t)(k0 + rr) * ldsrc + ncol); sv[i] = sc ? sc[k0 + rr] : 1.0f; }
; #pragma unroll
;       for (int i = 0; i < 8; ++i) { const int rr = r + 8 * i; t[rr * 257 + c4 + 0] = v[i][0] * sv[i]; t[rr * 257 + c4 + 1] = v[i][1] * sv[i]; t[rr * 257 + c4 + 2] = v[i][2] * sv[i]; t[rr * 257 + c4 + 3] = v[i][3] * sv[i]; } }
;     __syncthreads();
;     { const int nn = tid >> 1, kh = (tid & 1) * 32;
; #pragma unroll
;       for (int q = 0; q < 4; ++q) { float v[8];
; #pragma unroll
;           for (int j = 0; j < 8; ++j) v[j] = t[(kh + q * 8 + j) * 257 + nn];
;           u32x4 w; w.x = cvt_pk_bf16(v[0], v[1]); w.y = cvt_pk_bf16(v[2], v[3]); w.z = cvt_pk_bf16(v[4], v[5]); w.w = cvt_pk_bf16(v[6], v[7]);
;           *(u32x4*)(dst + (size_t)(n0 + nn) * dstld + k0 + kh + q * 8) = w; } }
;     __syncthreads();
; }
.LBB0_91:
	s_waitcnt vmcnt(7)
	v_pk_mul_f32 v[2:3], v[2:3], v[44:45] op_sel_hi:[1,0]
	ds_write2_b32 v53, v2, v3 offset1:1
	v_pk_mul_f32 v[2:3], v[4:5], v[44:45] op_sel_hi:[1,0]
	ds_write2_b32 v53, v2, v3 offset0:2 offset1:3
	s_waitcnt vmcnt(6)
	v_pk_mul_f32 v[2:3], v[6:7], v[42:43] op_sel_hi:[1,0]
	v_add_u32_e32 v4, 0x2020, v53
	ds_write2_b32 v4, v2, v3 offset1:1
	v_pk_mul_f32 v[2:3], v[8:9], v[42:43] op_sel_hi:[1,0]
	v_add_u32_e32 v4, 0x2028, v53
	ds_write2_b32 v4, v2, v3 offset1:1
	s_waitcnt vmcnt(5)
	v_pk_mul_f32 v[2:3], v[10:11], v[50:51] op_sel_hi:[1,0]
	v_add_u32_e32 v4, 0x4040, v53
	ds_write2_b32 v4, v2, v3 offset1:1
	v_pk_mul_f32 v[2:3], v[12:13], v[50:51] op_sel_hi:[1,0]
	v_add_u32_e32 v4, 0x4048, v53
	ds_write2_b32 v4, v2, v3 offset1:1
	s_waitcnt vmcnt(4)
	v_pk_mul_f32 v[2:3], v[14:15], v[46:47] op_sel_hi:[1,0]
	v_add_u32_e32 v4, 0x6060, v53
	ds_write2_b32 v4, v2, v3 offset1:1
	v_pk_mul_f32 v[2:3], v[16:17], v[46:47] op_sel_hi:[1,0]
	v_add_u32_e32 v4, 0x6068, v53
	ds_write2_b32 v4, v2, v3 offset1:1
	s_waitcnt vmcnt(3)
	v_pk_mul_f32 v[2:3], v[18:19], v[54:55] op_sel_hi:[1,0]
	v_add_u32_e32 v4, 0x8080, v53
	ds_write2_b32 v4, v2, v3 offset1:1
	v_pk_mul_f32 v[2:3], v[20:21], v[54:55] op_sel_hi:[1,0]
	v_add_u32_e32 v4, 0x8088, v53
	ds_write2_b32 v4, v2, v3 offset1:1
	s_waitcnt vmcnt(2)
	v_pk_mul_f32 v[2:3], v[22:23], v[52:53] op_sel_hi:[1,0]
	v_add_u32_e32 v4, 0xa0a0, v53
	ds_write2_b32 v4, v2, v3 offset1:1
	v_pk_mul_f32 v[2:3], v[24:25], v[52:53] op_sel_hi:[1,0]
	v_add_u32_e32 v4, 0xa0a8, v53
	ds_write2_b32 v4, v2, v3 offset1:1
	s_waitcnt vmcnt(1)
	v_pk_mul_f32 v[2:3], v[26:27], v[58:59] op_sel_hi:[1,0]
	v_add_u32_e32 v4, 0xc0c0, v53
	ds_write2_b32 v4, v2, v3 offset1:1
	v_pk_mul_f32 v[2:3], v[28:29], v[58:59] op_sel_hi:[1,0]
	v_add_u32_e32 v4, 0xc0c8, v53
	ds_write2_b32 v4, v2, v3 offset1:1
	s_waitcnt vmcnt(0)
	v_pk_mul_f32 v[2:3], v[30:31], v[56:57] op_sel_hi:[1,0]
	v_add_u32_e32 v4, 0xe0e0, v53
	ds_write2_b32 v4, v2, v3 offset1:1
	v_pk_mul_f32 v[2:3], v[32:33], v[56:57] op_sel_hi:[1,0]
	v_add_u32_e32 v4, 0xe0e8, v53
	ds_write2_b32 v4, v2, v3 offset1:1
	s_waitcnt lgkmcnt(0)
	s_barrier
	v_add_u32_e32 v2, s80, v55
	ds_read_b32 v4, v57
	ds_read_b32 v5, v57 offset:1028
	ds_read_b32 v8, v57 offset:2056
	ds_read_b32 v9, v57 offset:3084
	ds_read_b32 v10, v57 offset:4112
	ds_read_b32 v11, v57 offset:5140
	ds_read_b32 v12, v57 offset:6168
	ds_read_b32 v13, v57 offset:7196
	v_ashrrev_i32_e32 v3, 31, v2
	s_add_i32 s0, s39, s0
	v_lshlrev_b64 v[2:3], 11, v[2:3]
	v_lshl_add_u64 v[2:3], s[64:65], 0, v[2:3]
	s_ashr_i32 s1, s0, 31
	v_lshl_add_u64 v[2:3], s[0:1], 1, v[2:3]
	v_lshl_add_u64 v[6:7], v[2:3], 0, v[34:35]
	s_waitcnt lgkmcnt(6)
	v_cvt_pk_bf16_f32 v2, v4, v5
	s_waitcnt lgkmcnt(4)
	v_cvt_pk_bf16_f32 v3, v8, v9
	s_waitcnt lgkmcnt(2)
	v_cvt_pk_bf16_f32 v4, v10, v11
	s_waitcnt lgkmcnt(0)
	v_cvt_pk_bf16_f32 v5, v12, v13
	ds_read_b32 v8, v57 offset:8224
	ds_read_b32 v9, v57 offset:9252
	ds_read_b32 v10, v57 offset:10280
	ds_read_b32 v11, v57 offset:11308
	ds_read_b32 v12, v57 offset:12336
	ds_read_b32 v13, v57 offset:13364
	ds_read_b32 v14, v57 offset:14392
	ds_read_b32 v15, v57 offset:15420
	global_store_dwordx4 v[6:7], v[2:5], off nt
	s_add_i32 s26, s26, s88
	s_add_i32 s39, s39, s5
	s_waitcnt lgkmcnt(6)
	v_cvt_pk_bf16_f32 v2, v8, v9
	s_waitcnt lgkmcnt(4)
	v_cvt_pk_bf16_f32 v3, v10, v11
	s_waitcnt lgkmcnt(2)
	v_cvt_pk_bf16_f32 v4, v12, v13
	s_waitcnt lgkmcnt(0)
	v_cvt_pk_bf16_f32 v5, v14, v15
	ds_read_b32 v8, v57 offset:16448
	ds_read_b32 v9, v57 offset:17476
	ds_read_b32 v10, v57 offset:18504
	ds_read_b32 v11, v57 offset:19532
	ds_read_b32 v12, v57 offset:20560
	ds_read_b32 v13, v57 offset:21588
	ds_read_b32 v14, v57 offset:22616
	ds_read_b32 v15, v57 offset:23644
	global_store_dwordx4 v[6:7], v[2:5], off offset:16 nt
	s_cmp_lt_i32 s26, 64
	s_waitcnt lgkmcnt(6)
	v_cvt_pk_bf16_f32 v2, v8, v9
	s_waitcnt lgkmcnt(4)
	v_cvt_pk_bf16_f32 v3, v10, v11
	s_waitcnt lgkmcnt(2)
	v_cvt_pk_bf16_f32 v4, v12, v13
	s_waitcnt lgkmcnt(0)
	v_cvt_pk_bf16_f32 v5, v14, v15
	ds_read_b32 v8, v57 offset:24672
	ds_read_b32 v9, v57 offset:25700
	ds_read_b32 v10, v57 offset:26728
	ds_read_b32 v11, v57 offset:27756
	ds_read_b32 v12, v57 offset:28784
	ds_read_b32 v13, v57 offset:29812
	ds_read_b32 v14, v57 offset:30840
	ds_read_b32 v15, v57 offset:31868
	global_store_dwordx4 v[6:7], v[2:5], off offset:32 nt
	s_waitcnt lgkmcnt(6)
	s_nop 0
	v_cvt_pk_bf16_f32 v2, v8, v9
	s_waitcnt lgkmcnt(4)
	v_cvt_pk_bf16_f32 v3, v10, v11
	s_waitcnt lgkmcnt(2)
	v_cvt_pk_bf16_f32 v4, v12, v13
	s_waitcnt lgkmcnt(0)
	v_cvt_pk_bf16_f32 v5, v14, v15
	global_store_dwordx4 v[6:7], v[2:5], off offset:48 nt
	s_barrier
	s_cbranch_scc0 .LBB0_108

; #define LAS __attribute__((address_space(3)))
; __device__ __forceinline__ unsigned cvt_pk_bf16(float lo, float hi) { const f32x2 v = {lo, hi}; return __builtin_bit_cast(unsigned, __builtin_convertvector(v, bfx2_t)); }
; __device__ __forceinline__ void convT_tile(const float* src, int ldsrc, const float* sc, bf16_t* dst, int dstld, int k0, int n0, int swiglu, LAS float* t) {
;     const int tid = threadIdx.x;
;     { const int r = tid >> 6, c4 = (tid & 63) * 4;
;       int ncol = n0 + c4; if (swiglu) { const int blk = n0 >> 8; ncol = (c4 < 128) ? (128 * blk + c4) : (FF + 128 * blk + (c4 - 128)); }
;       f32x4 v[8]; float sv[8];
; #pragma unroll
;       for (int i = 0; i < 8; ++i) { const int rr = r + 8 * i; v[i] = *(const f32x4*)(src + (size_t)(k0 + rr) * ldsrc + ncol); sv[i] = sc ? sc[k0 + rr] : 1.0f; }
; #pragma unroll
;       for (int i = 0; i < 8; ++i) { const int rr = r + 8 * i; t[rr * 257 + c4 + 0] = v[i][0] * sv[i]; t[rr * 257 + c4 + 1] = v[i][1] * sv[i]; t[rr * 257 + c4 + 2] = v[i][2] * sv[i]; t[rr * 257 + c4 + 3] = v[i][3] * sv[i]; } }
;     __syncthreads();
;     { const int nn = tid >> 1, kh = (tid & 1) * 32;
; #pragma unroll
;       for (int q = 0; q < 4; ++q) { float v[8];
; #pragma unroll
;           for (int j = 0; j < 8; ++j) v[j] = t[(kh + q * 8 + j) * 257 + nn];
;           u32x4 w; w.x = cvt_pk_bf16(v[0], v[1]); w.y = cvt_pk_bf16(v[2], v[3]); w.z = cvt_pk_bf16(v[4], v[5]); w.w = cvt_pk_bf16(v[6], v[7]);
;           *(u32x4*)(dst + (size_t)(n0 + nn) * dstld + k0 + kh + q * 8) = w; } }
;     __syncthreads();
; }
.LBB0_110:
	s_ashr_i32 s42, s26, 31
	s_lshr_b32 s42, s42, 30
	s_add_i32 s42, s26, s42
	s_lshl_b32 s42, s42, 6
	s_and_b32 s43, s42, 0xffffff00
	s_sub_i32 s42, s39, s43
	v_or_b32_e32 v2, s43, v45
	v_add_u32_e32 v4, s42, v37
	v_ashrrev_i32_e32 v3, 31, v2
	v_lshl_add_u64 v[6:7], v[2:3], 2, s[0:1]
	v_add_u32_e32 v2, 8, v4
	v_add_u32_e32 v8, 16, v4
	v_add_u32_e32 v10, 24, v4
	v_add_u32_e32 v12, 32, v4
	v_add_u32_e32 v14, 40, v4
	v_add_u32_e32 v16, 48, v4
	v_add_u32_e32 v18, 56, v4
	v_ashrrev_i32_e32 v5, 31, v4
	v_ashrrev_i32_e32 v3, 31, v2
	v_ashrrev_i32_e32 v9, 31, v8
	v_ashrrev_i32_e32 v11, 31, v10
	v_ashrrev_i32_e32 v13, 31, v12
	v_ashrrev_i32_e32 v15, 31, v14
	v_ashrrev_i32_e32 v17, 31, v16
	v_ashrrev_i32_e32 v19, 31, v18
	v_lshlrev_b64 v[4:5], 12, v[4:5]
	v_lshlrev_b64 v[20:21], 12, v[2:3]
	v_lshlrev_b64 v[8:9], 12, v[8:9]
	v_lshlrev_b64 v[10:11], 12, v[10:11]
	v_lshlrev_b64 v[12:13], 12, v[12:13]
	v_lshlrev_b64 v[14:15], 12, v[14:15]
	v_lshlrev_b64 v[16:17], 12, v[16:17]
	v_lshlrev_b64 v[18:19], 12, v[18:19]
	v_lshl_add_u64 v[4:5], v[6:7], 0, v[4:5]
	v_lshl_add_u64 v[20:21], v[6:7], 0, v[20:21]
	v_lshl_add_u64 v[22:23], v[6:7], 0, v[8:9]
	v_lshl_add_u64 v[24:25], v[6:7], 0, v[10:11]
	v_lshl_add_u64 v[26:27], v[6:7], 0, v[12:13]
	v_lshl_add_u64 v[28:29], v[6:7], 0, v[14:15]
	v_lshl_add_u64 v[30:31], v[6:7], 0, v[16:17]
	v_lshl_add_u64 v[32:33], v[6:7], 0, v[18:19]
	global_load_dwordx4 v[2:5], v[4:5], off nt
	s_nop 0
	global_load_dwordx4 v[6:9], v[20:21], off nt
	global_load_dwordx4 v[10:13], v[22:23], off nt
	global_load_dwordx4 v[14:17], v[24:25], off nt
	s_nop 0
	global_load_dwordx4 v[18:21], v[26:27], off nt
	global_load_dwordx4 v[22:25], v[28:29], off nt
	s_nop 0
	global_load_dwordx4 v[26:29], v[30:31], off nt
	s_nop 0
	global_load_dwordx4 v[30:33], v[32:33], off nt
	v_add_u32_e32 v48, s43, v55
	v_add_u32_e32 v41, 0x2020, v53
	v_add_u32_e32 v42, 0x2028, v53
	v_add_u32_e32 v44, 0x4040, v53
	v_add_u32_e32 v46, 0x4048, v53
	v_add_u32_e32 v50, 0x6060, v53
	v_add_u32_e32 v51, 0x6068, v53
	v_add_u32_e32 v52, 0x8080, v53
	v_add_u32_e32 v54, 0x8088, v53
	v_add_u32_e32 v56, 0xa0a0, v53
	v_add_u32_e32 v58, 0xa0a8, v53
	v_add_u32_e32 v65, 0xc0c0, v53
	v_add_u32_e32 v66, 0xc0c8, v53
	v_add_u32_e32 v67, 0xe0e0, v53
	v_add_u32_e32 v68, 0xe0e8, v53
	v_ashrrev_i32_e32 v49, 31, v48
	v_lshlrev_b64 v[48:49], 9, v[48:49]
	s_ashr_i32 s43, s42, 31
	v_lshl_add_u64 v[48:49], s[40:41], 0, v[48:49]
	s_add_i32 s26, s26, s88
	s_add_i32 s39, s39, s5
	v_lshl_add_u64 v[48:49], s[42:43], 1, v[48:49]
	s_cmp_lt_i32 s26, 16
	v_lshl_add_u64 v[48:49], v[48:49], 0, v[34:35]
	s_waitcnt vmcnt(7)
	ds_write2_b32 v53, v2, v3 offset1:1
	ds_write2_b32 v53, v4, v5 offset0:2 offset1:3
	s_waitcnt vmcnt(6)
	ds_write2_b32 v41, v6, v7 offset1:1
	ds_write2_b32 v42, v8, v9 offset1:1
	s_waitcnt vmcnt(5)
	ds_write2_b32 v44, v10, v11 offset1:1
	ds_write2_b32 v46, v12, v13 offset1:1
	s_waitcnt vmcnt(4)
	ds_write2_b32 v50, v14, v15 offset1:1
	ds_write2_b32 v51, v16, v17 offset1:1
	s_waitcnt vmcnt(3)
	ds_write2_b32 v52, v18, v19 offset1:1
	ds_write2_b32 v54, v20, v21 offset1:1
	s_waitcnt vmcnt(2)
	ds_write2_b32 v56, v22, v23 offset1:1
	ds_write2_b32 v58, v24, v25 offset1:1
	s_waitcnt vmcnt(1)
	ds_write2_b32 v65, v26, v27 offset1:1
	ds_write2_b32 v66, v28, v29 offset1:1
	s_waitcnt vmcnt(0)
	ds_write2_b32 v67, v30, v31 offset1:1
	ds_write2_b32 v68, v32, v33 offset1:1
	s_waitcnt lgkmcnt(0)
	s_barrier
	ds_read_b32 v2, v57
	ds_read_b32 v3, v57 offset:1028
	ds_read_b32 v4, v57 offset:2056
	ds_read_b32 v5, v57 offset:3084
	ds_read_b32 v6, v57 offset:4112
	ds_read_b32 v7, v57 offset:5140
	ds_read_b32 v8, v57 offset:6168
	ds_read_b32 v9, v57 offset:7196
	ds_read_b32 v10, v57 offset:8224
	ds_read_b32 v11, v57 offset:9252
	ds_read_b32 v12, v57 offset:10280
	ds_read_b32 v13, v57 offset:11308
	ds_read_b32 v14, v57 offset:12336
	ds_read_b32 v15, v57 offset:13364
	ds_read_b32 v16, v57 offset:14392
	ds_read_b32 v17, v57 offset:15420
	ds_read_b32 v18, v57 offset:16448
	ds_read_b32 v19, v57 offset:17476
	ds_read_b32 v20, v57 offset:18504
	ds_read_b32 v21, v57 offset:19532
	ds_read_b32 v22, v57 offset:20560
	ds_read_b32 v23, v57 offset:21588
	ds_read_b32 v24, v57 offset:22616
	ds_read_b32 v25, v57 offset:23644
	ds_read_b32 v26, v57 offset:24672
	ds_read_b32 v27, v57 offset:25700
	ds_read_b32 v28, v57 offset:26728
	ds_read_b32 v29, v57 offset:27756
	ds_read_b32 v30, v57 offset:28784
	ds_read_b32 v31, v57 offset:29812
	ds_read_b32 v32, v57 offset:30840
	ds_read_b32 v33, v57 offset:31868
	s_waitcnt lgkmcnt(14)
	v_cvt_pk_bf16_f32 v2, v2, v3
	v_cvt_pk_bf16_f32 v3, v4, v5
	v_cvt_pk_bf16_f32 v4, v6, v7
	v_cvt_pk_bf16_f32 v5, v8, v9
	v_cvt_pk_bf16_f32 v6, v10, v11
	v_cvt_pk_bf16_f32 v7, v12, v13
	v_cvt_pk_bf16_f32 v8, v14, v15
	v_cvt_pk_bf16_f32 v9, v16, v17
	v_cvt_pk_bf16_f32 v10, v18, v19
	s_waitcnt lgkmcnt(12)
	v_cvt_pk_bf16_f32 v11, v20, v21
	s_waitcnt lgkmcnt(10)
	v_cvt_pk_bf16_f32 v12, v22, v23
	s_waitcnt lgkmcnt(8)
	v_cvt_pk_bf16_f32 v13, v24, v25
	s_waitcnt lgkmcnt(6)
	v_cvt_pk_bf16_f32 v14, v26, v27
	s_waitcnt lgkmcnt(4)
	v_cvt_pk_bf16_f32 v15, v28, v29
	s_waitcnt lgkmcnt(2)
	v_cvt_pk_bf16_f32 v16, v30, v31
	s_waitcnt lgkmcnt(0)
	v_cvt_pk_bf16_f32 v17, v32, v33
	global_store_dwordx4 v[48:49], v[2:5], off nt
	global_store_dwordx4 v[48:49], v[6:9], off offset:16 nt
	global_store_dwordx4 v[48:49], v[10:13], off offset:32 nt
	global_store_dwordx4 v[48:49], v[14:17], off offset:48 nt
	s_barrier
	s_cbranch_scc1 .LBB0_110
	s_branch .LBB0_14
